# comb6 + all 6 main GEMM K-loops: early wave group gets own loop copy with vmcnt(8) deferred to end of MFMA block
# baseline (speedup 1.0000x reference)
;     __host__ __device__ bool next(int i, Unit& u) const { const bool ok = StaticOrder::next(i >> 1, u); if (i & 1) { u.ka = D_INNER; u.nkt = D_ATT / BK; } else { u.ka = 0; u.nkt = D_INNER / BK; } return ok; }
;     __host__ __device__ bool next(int i, Unit& u) const { const long L = (long)i * G + c; if (L >= (long)nM * nS) return false; u.pm = (int)(L % nM); u.pn = 0; u.ka = (int)(L / nM) * kslab; u.nkt = kslab / BK; return true; }
;     __host__ __device__ bool next(int i, Unit& u) const { if (i > 0) return false; const int x = c & 7, j = c >> 3; u.pm = 16 * s + 4 * (x >> 1) + (j & 3); u.pn = 8 * (x & 1) + (j >> 2); u.ka = 0; u.nkt = nkt; return true; }
; #define PG8_STAGE(bufoff, gbase, voff) do { _Pragma("unroll") for (int _i = 0; _i < 2; ++_i) \
;         __builtin_amdgcn_global_load_lds((const unsigned*)((const char*)(gbase) + (voff)[_i]), (LAS unsigned*)(lds + (bufoff) + ldsw + _i * 8192), 16, 0, 0); } while (0)
; #define PG8_WAIT_V(n) asm volatile("s_waitcnt vmcnt(" #n ")" ::: "memory")
; template <class Epi, class Sched, bool ALIGN_EPI, class Hook = NoHook>
; __device__ __forceinline__ void gemm_phase(LAS unsigned char* lds, const Gemm g, const Sched& S, const Epi& E, const Hook& H = Hook()) {
;     ...
;     const int aoff = lds_byte(wr * 64 + fr, fq * 8), boff = lds_byte(wc * 32 + fr, fq * 8);
;     ...
;     Unit cur, nxt; int ui = 0;
;     if (!S.next(0, cur)) return;
;     f32x4 acc[2][2][4][2];
; #pragma unroll
;     for (int a = 0; a < 2; ++a)
; #pragma unroll
;         for (int b = 0; b < 2; ++b)
; #pragma unroll
;             for (int m = 0; m < 4; ++m)
; #pragma unroll
;                 for (int n = 0; n < 2; ++n) acc[a][b][m][n] = (f32x4){0.f, 0.f, 0.f, 0.f};
;     bf16x8 At[4][2], B0[2][2], B1[2][2];
;     const char* cA = (const char*)g.A + (size_t)cur.pm * tA + (size_t)cur.ka * 2; const char* cB = (const char*)g.Bt + (size_t)cur.pn * 2 * hB + (size_t)cur.ka * 2;
;     S.a_ready(cur);
;     if constexpr (Hook::ON) H.unit_start(cur);
;     PG8_STAGE(PG8_SB(0, 0), cB, voffB); PG8_STAGE(PG8_SB(0, 1), cB + hB, voffB); PG8_STAGE(PG8_SA(0, 0), cA, voffA); PG8_STAGE(PG8_SA(0, 1), cA + hA, voffA);
;     if (wr == 1) PG8_BAR;
;     PG8_WAIT_V(2); PG8_BAR;
;     PG8_STAGE(PG8_SB(1, 0), cB + kstep, voffB); PG8_STAGE(PG8_SA(1, 0), cA + kstep, voffA); PG8_STAGE(PG8_SB(1, 1), cB + hB + kstep, voffB);
;     PG8_WAIT_V(6); PG8_BAR;
.LBB0_849:
	v_and_b32_e32 v181, 15, v180
	v_and_b32_e32 v15, 48, v180
	v_lshlrev_b32_e32 v16, 2, v180
	s_and_b32 s27, s24, 3
	s_lshl_b32 s4, s25, 13
	v_lshl_or_b32 v15, v181, 6, v15
	v_and_b32_e32 v16, 32, v16
	v_bitop3_b32 v17, v15, s4, v16 bitop3:0xde
	s_lshl_b32 s4, s27, 12
	v_bitop3_b32 v15, v15, s4, v16 bitop3:0xde
	s_mov_b64 s[4:5], 0x80
	s_add_i32 m0, s28, 0x18000
	v_lshl_add_u64 v[8:9], v[8:9], 0, s[4:5]
	s_waitcnt vmcnt(2)
	s_barrier
	global_load_lds_dwordx4 v[8:9], off
	v_lshl_add_u64 v[6:7], v[6:7], 0, s[4:5]
	s_add_i32 m0, s28, 0x1a000
	s_add_i32 s40, s28, 0x8000
	s_add_i32 s41, s28, 0xa000
	global_load_lds_dwordx4 v[6:7], off
	v_lshl_add_u64 v[4:5], v[4:5], 0, s[4:5]
	s_mov_b32 m0, s40
	s_add_u32 s18, s14, 0x100080
	global_load_lds_dwordx4 v[4:5], off
	v_lshl_add_u64 v[2:3], v[2:3], 0, s[4:5]
	s_mov_b32 m0, s41
	s_addc_u32 s19, s15, 0
	global_load_lds_dwordx4 v[2:3], off
	s_add_i32 m0, s28, 0x1c000
	v_lshl_add_u64 v[2:3], s[18:19], 0, v[132:133]
	global_load_lds_dwordx4 v[2:3], off
	v_lshl_add_u64 v[2:3], s[18:19], 0, v[136:137]
	s_add_i32 m0, s28, 0x1e000
	s_lshl_b32 s6, s88, 22
	global_load_lds_dwordx4 v[2:3], off
	v_lshlrev_b32_e32 v2, 16, v1
	v_and_b32_e32 v2, 0xfffe0000, v2
	v_lshl_add_u32 v2, v10, 13, v2
	v_and_b32_e32 v1, 1, v1
	s_and_b32 s6, s6, 0x1800000
	s_lshl_b32 s7, s33, 21
	v_lshl_or_b32 v1, v1, 6, v2
	s_or_b32 s6, s6, s7
	v_lshl_add_u32 v2, v11, 1, v1
	s_add_u32 s6, s96, s6
	v_lshlrev_b32_e32 v1, 16, v12
	v_mov_b32_e32 v3, v133
	s_addc_u32 s7, s97, 0
	v_and_b32_e32 v1, 0xfffe0000, v1
	v_lshl_add_u64 v[138:139], s[6:7], 0, v[2:3]
	v_lshl_add_u32 v1, v13, 13, v1
	v_and_b32_e32 v2, 1, v12
	s_waitcnt vmcnt(6)
	v_lshl_or_b32 v1, v2, 6, v1
	s_add_i32 s34, 0, 0x10000
	s_add_i32 s35, 0, 0x14000
	s_add_i32 s36, 0, 0x18000
	s_add_i32 s37, 0, 0x1c000
	v_lshl_add_u32 v2, v14, 1, v1
	s_add_i32 s45, s34, s20
	s_add_i32 s47, s35, s20
	s_add_i32 s49, s36, s20
	s_add_i32 s51, s37, s20
	v_lshl_or_b32 v185, s25, 6, v181
	v_lshl_add_u64 v[140:141], s[6:7], 0, v[2:3]
	s_mov_b32 s42, -2
	s_mov_b64 s[6:7], 0x78400080
	v_add_u32_e32 v1, s34, v15
	v_add_u32_e32 v142, s35, v15
	v_add_u32_e32 v143, 0, v17
	s_add_i32 s43, s28, 0xc000
	s_add_i32 s44, s28, 0xe000
	s_add_i32 s46, s45, 0x2000
	s_add_i32 s48, s47, 0x2000
	v_add_u32_e32 v144, s36, v15
	v_add_u32_e32 v145, s37, v15
	s_add_i32 s50, s49, 0x2000
	s_add_i32 s52, s51, 0x2000
	v_mov_b32_e32 v114, v133
	v_mov_b32_e32 v115, v133
	v_mov_b32_e32 v116, v133
	v_mov_b32_e32 v117, v133
	v_mov_b32_e32 v118, v133
	v_mov_b32_e32 v119, v133
	v_mov_b32_e32 v120, v133
	v_mov_b32_e32 v121, v133
	v_mov_b32_e32 v82, v133
	v_mov_b32_e32 v83, v133
	v_mov_b32_e32 v84, v133
	v_mov_b32_e32 v85, v133
	v_mov_b32_e32 v90, v133
	v_mov_b32_e32 v91, v133
	v_mov_b32_e32 v92, v133
	v_mov_b32_e32 v93, v133
	v_mov_b32_e32 v66, v133
	v_mov_b32_e32 v67, v133
	v_mov_b32_e32 v68, v133
	v_mov_b32_e32 v69, v133
	v_mov_b32_e32 v74, v133
	v_mov_b32_e32 v75, v133
	v_mov_b32_e32 v76, v133
	v_mov_b32_e32 v77, v133
	v_mov_b32_e32 v46, v133
	v_mov_b32_e32 v47, v133
	v_mov_b32_e32 v48, v133
	v_mov_b32_e32 v49, v133
	v_mov_b32_e32 v58, v133
	v_mov_b32_e32 v59, v133
	v_mov_b32_e32 v60, v133
	v_mov_b32_e32 v61, v133
	v_mov_b32_e32 v122, v133
	v_mov_b32_e32 v123, v133
	v_mov_b32_e32 v124, v133
	v_mov_b32_e32 v125, v133
	v_mov_b32_e32 v126, v133
	v_mov_b32_e32 v127, v133
	v_mov_b32_e32 v128, v133
	v_mov_b32_e32 v129, v133
	v_mov_b32_e32 v106, v133
	v_mov_b32_e32 v107, v133
	v_mov_b32_e32 v108, v133
	v_mov_b32_e32 v109, v133
	v_mov_b32_e32 v110, v133
	v_mov_b32_e32 v111, v133
	v_mov_b32_e32 v112, v133
	v_mov_b32_e32 v113, v133
	v_mov_b32_e32 v98, v133
	v_mov_b32_e32 v99, v133
	v_mov_b32_e32 v100, v133
	v_mov_b32_e32 v101, v133
	v_mov_b32_e32 v102, v133
	v_mov_b32_e32 v103, v133
	v_mov_b32_e32 v104, v133
	v_mov_b32_e32 v105, v133
	v_mov_b32_e32 v86, v133
	v_mov_b32_e32 v87, v133
	v_mov_b32_e32 v88, v133
	v_mov_b32_e32 v89, v133
	v_mov_b32_e32 v94, v133
	v_mov_b32_e32 v95, v133
	v_mov_b32_e32 v96, v133
	v_mov_b32_e32 v97, v133
	v_mov_b32_e32 v26, v133
	v_mov_b32_e32 v27, v133
	v_mov_b32_e32 v28, v133
	v_mov_b32_e32 v29, v133
	v_mov_b32_e32 v38, v133
	v_mov_b32_e32 v39, v133
	v_mov_b32_e32 v40, v133
	v_mov_b32_e32 v41, v133
	v_mov_b32_e32 v18, v133
	v_mov_b32_e32 v19, v133
	v_mov_b32_e32 v20, v133
	v_mov_b32_e32 v21, v133
	v_mov_b32_e32 v22, v133
	v_mov_b32_e32 v23, v133
	v_mov_b32_e32 v24, v133
	v_mov_b32_e32 v25, v133
	v_mov_b32_e32 v6, v133
	v_mov_b32_e32 v7, v133
	v_mov_b32_e32 v8, v133
	v_mov_b32_e32 v9, v133
	v_mov_b32_e32 v14, v133
	v_mov_b32_e32 v15, v133
	v_mov_b32_e32 v16, v133
	v_mov_b32_e32 v17, v133
	v_mov_b32_e32 v2, v133
	v_mov_b32_e32 v4, v133
	v_mov_b32_e32 v5, v133
	v_mov_b32_e32 v10, v133
	v_mov_b32_e32 v11, v133
	v_mov_b32_e32 v12, v133
	v_mov_b32_e32 v13, v133
	v_mov_b32_e32 v70, v133
	v_mov_b32_e32 v71, v133
	v_mov_b32_e32 v72, v133
	v_mov_b32_e32 v73, v133
	v_mov_b32_e32 v78, v133
	v_mov_b32_e32 v79, v133
	v_mov_b32_e32 v80, v133
	v_mov_b32_e32 v81, v133
	v_mov_b32_e32 v50, v133
	v_mov_b32_e32 v51, v133
	v_mov_b32_e32 v52, v133
	v_mov_b32_e32 v53, v133
	v_mov_b32_e32 v62, v133
	v_mov_b32_e32 v63, v133
	v_mov_b32_e32 v64, v133
	v_mov_b32_e32 v65, v133
	v_mov_b32_e32 v30, v133
	v_mov_b32_e32 v31, v133
	v_mov_b32_e32 v32, v133
	v_mov_b32_e32 v33, v133
	v_mov_b32_e32 v42, v133
	v_mov_b32_e32 v43, v133
	v_mov_b32_e32 v44, v133
	v_mov_b32_e32 v45, v133
	v_mov_b32_e32 v34, v133
	v_mov_b32_e32 v35, v133
	v_mov_b32_e32 v36, v133
	v_mov_b32_e32 v37, v133
	v_mov_b32_e32 v54, v133
	v_mov_b32_e32 v55, v133
	v_mov_b32_e32 v56, v133
	v_mov_b32_e32 v57, v133
	s_barrier
	s_cmpk_lt_u32 s26, 0x100
	s_cbranch_scc0 .Lmy_d850B
; #define PG8_STAGE(bufoff, gbase, voff) do { _Pragma("unroll") for (int _i = 0; _i < 2; ++_i) \
;         __builtin_amdgcn_global_load_lds((const unsigned*)((const char*)(gbase) + (voff)[_i]), (LAS unsigned*)(lds + (bufoff) + ldsw + _i * 8192), 16, 0, 0); } while (0)
; #define PG8_LDA(dst, b, h) do { _Pragma("unroll") for (int m = 0; m < 4; ++m) _Pragma("unroll") for (int k = 0; k < 2; ++k) dst[m][k] = *(const LAS bf16x8*)(lds + PG8_SA(b, h) + aoff + m * 2048 + k * 1024); } while (0)
; #define PG8_LDB(dst, b, h) do { _Pragma("unroll") for (int n = 0; n < 2; ++n) _Pragma("unroll") for (int k = 0; k < 2; ++k) dst[n][k] = *(const LAS bf16x8*)(lds + PG8_SB(b, h) + boff + n * 2048 + k * 1024); } while (0)
; #define PG8_MMA(ai, bj, At, Bt) do { __builtin_amdgcn_s_setprio(1); _Pragma("unroll") for (int m = 0; m < 4; ++m) _Pragma("unroll") for (int n = 0; n < 2; ++n) _Pragma("unroll") for (int k = 0; k < 2; ++k) \
;         acc[ai][bj][m][n] = __builtin_amdgcn_mfma_f32_16x16x32_bf16(Bt[n][k], At[m][k], acc[ai][bj][m][n], 0, 0, 0); __builtin_amdgcn_s_setprio(0); } while (0)
; #define PG8_WAIT_V(n) asm volatile("s_waitcnt vmcnt(" #n ")" ::: "memory")
; #define PG8_WAIT_L(n) asm volatile("s_waitcnt lgkmcnt(" #n ")" ::: "memory")
; #define PG8_BAR __builtin_amdgcn_s_barrier()
; template <class Epi, class Sched, bool ALIGN_EPI, class Hook = NoHook>
; __device__ __forceinline__ void gemm_phase(LAS unsigned char* lds, const Gemm g, const Sched& S, const Epi& E, const Hook& H = Hook()) {
;     ...
;             const bool last = (t == nt - 2);
;             const char* a1 = cA + (size_t)(t + 1) * kstep;
;             const char* a2 = last ? nA : cA + (size_t)(t + 2) * kstep; const char* b2 = last ? nB : cB + (size_t)(t + 2) * kstep;
;             const char* a3 = a2 + kstep; const char* b3 = b2 + kstep;
;             if (last && has_next) S.a_ready(nxt);
;             PG8_LDB(B0, 0, 0); PG8_LDB(B1, 0, 1); PG8_SCHED; PG8_LDA(At, 0, 0); PG8_STAGE(PG8_SA(1, 1), a1 + hA, voffA);
;             PG8_WAIT_V(8); PG8_WAIT_L(0); PG8_BAR; PG8_MMA(0, 0, At, B0); PG8_MMA(0, 1, At, B1); PG8_BAR; PG8_SCHED;
;             PG8_LDA(At, 0, 1); PG8_STAGE(PG8_SB(0, 0), b2, voffB); PG8_STAGE(PG8_SB(0, 1), b2 + hB, voffB); PG8_STAGE(PG8_SA(0, 0), a2, voffA);
;             PG8_WAIT_V(8); PG8_WAIT_L(0); PG8_BAR; PG8_MMA(1, 0, At, B0); PG8_MMA(1, 1, At, B1); PG8_BAR; PG8_SCHED;
.LBB0_850:
	ds_read_b128 v[146:149], v1
	ds_read_b128 v[150:153], v1 offset:1024
	s_add_u32 s20, s6, 0x87c00080
	s_addc_u32 s21, s7, -1
	s_cmp_lg_u32 s42, 60
	s_cselect_b32 s20, s20, 0
	s_cselect_b32 s21, s21, 0
	s_add_u32 s22, s2, s20
	s_addc_u32 s23, s3, s21
	s_add_u32 s20, s14, s20
	s_addc_u32 s21, s15, s21
	s_mov_b32 m0, s43
	ds_read_b128 v[154:157], v1 offset:2048
	ds_read_b128 v[158:161], v1 offset:3072
	ds_read_b128 v[162:165], v142
	ds_read_b128 v[166:169], v142 offset:1024
	ds_read_b128 v[170:173], v142 offset:2048
	ds_read_b128 v[174:177], v142 offset:3072
	v_lshl_add_u64 v[178:179], v[138:139], 0, s[6:7]
	global_load_lds_dwordx4 v[178:179], off
	ds_read_b128 v[186:189], v143
	ds_read_b128 v[190:193], v143 offset:1024
	ds_read_b128 v[194:197], v143 offset:2048
	ds_read_b128 v[198:201], v143 offset:3072
	ds_read_b128 v[202:205], v143 offset:4096
	ds_read_b128 v[206:209], v143 offset:5120
	ds_read_b128 v[210:213], v143 offset:6144
	ds_read_b128 v[214:217], v143 offset:7168
	v_lshl_add_u64 v[178:179], v[140:141], 0, s[6:7]
	s_mov_b32 m0, s44
	s_nop 0
	global_load_lds_dwordx4 v[178:179], off
	s_waitcnt lgkmcnt(0)
	s_barrier
	s_setprio 1
	s_waitcnt lgkmcnt(0)
	v_mfma_f32_16x16x32_bf16 v[54:57], v[146:149], v[186:189], v[54:57]
	v_mfma_f32_16x16x32_bf16 v[34:37], v[154:157], v[186:189], v[34:37]
	v_mfma_f32_16x16x32_bf16 v[42:45], v[146:149], v[194:197], v[42:45]
	v_mfma_f32_16x16x32_bf16 v[30:33], v[154:157], v[194:197], v[30:33]
	v_mfma_f32_16x16x32_bf16 v[62:65], v[146:149], v[202:205], v[62:65]
	v_mfma_f32_16x16x32_bf16 v[50:53], v[154:157], v[202:205], v[50:53]
	v_mfma_f32_16x16x32_bf16 v[78:81], v[146:149], v[210:213], v[78:81]
	v_mfma_f32_16x16x32_bf16 v[70:73], v[154:157], v[210:213], v[70:73]
	v_mfma_f32_16x16x32_bf16 v[54:57], v[150:153], v[190:193], v[54:57]
	v_mfma_f32_16x16x32_bf16 v[34:37], v[158:161], v[190:193], v[34:37]
	v_mfma_f32_16x16x32_bf16 v[42:45], v[150:153], v[198:201], v[42:45]
	v_mfma_f32_16x16x32_bf16 v[30:33], v[158:161], v[198:201], v[30:33]
	v_mfma_f32_16x16x32_bf16 v[62:65], v[150:153], v[206:209], v[62:65]
	v_mfma_f32_16x16x32_bf16 v[50:53], v[158:161], v[206:209], v[50:53]
	v_mfma_f32_16x16x32_bf16 v[78:81], v[150:153], v[214:217], v[78:81]
	v_mfma_f32_16x16x32_bf16 v[70:73], v[158:161], v[214:217], v[70:73]
	s_setprio 0
	s_setprio 1
	v_mfma_f32_16x16x32_bf16 v[10:13], v[162:165], v[186:189], v[10:13]
	v_mfma_f32_16x16x32_bf16 v[2:5], v[170:173], v[186:189], v[2:5]
	v_mfma_f32_16x16x32_bf16 v[14:17], v[162:165], v[194:197], v[14:17]
	v_mfma_f32_16x16x32_bf16 v[6:9], v[170:173], v[194:197], v[6:9]
	v_mfma_f32_16x16x32_bf16 v[22:25], v[162:165], v[202:205], v[22:25]
	v_mfma_f32_16x16x32_bf16 v[18:21], v[170:173], v[202:205], v[18:21]
	v_mfma_f32_16x16x32_bf16 v[38:41], v[162:165], v[210:213], v[38:41]
	v_mfma_f32_16x16x32_bf16 v[26:29], v[170:173], v[210:213], v[26:29]
	v_mfma_f32_16x16x32_bf16 v[10:13], v[166:169], v[190:193], v[10:13]
	v_mfma_f32_16x16x32_bf16 v[2:5], v[174:177], v[190:193], v[2:5]
	v_mfma_f32_16x16x32_bf16 v[14:17], v[166:169], v[198:201], v[14:17]
	v_mfma_f32_16x16x32_bf16 v[6:9], v[174:177], v[198:201], v[6:9]
	v_mfma_f32_16x16x32_bf16 v[22:25], v[166:169], v[206:209], v[22:25]
	v_mfma_f32_16x16x32_bf16 v[18:21], v[174:177], v[206:209], v[18:21]
	v_mfma_f32_16x16x32_bf16 v[38:41], v[166:169], v[214:217], v[38:41]
	v_mfma_f32_16x16x32_bf16 v[26:29], v[174:177], v[214:217], v[26:29]
	s_setprio 0
	s_waitcnt vmcnt(8)
	s_barrier
	s_mov_b32 m0, s45
	s_add_u32 s54, s20, 0x100000
	ds_read_b128 v[186:189], v143 offset:16384
	ds_read_b128 v[190:193], v143 offset:17408
	global_load_lds_dwordx4 v132, s[20:21]
	ds_read_b128 v[194:197], v143 offset:18432
	s_mov_b32 m0, s46
	s_addc_u32 s55, s21, 0
	global_load_lds_dwordx4 v136, s[20:21]
	ds_read_b128 v[198:201], v143 offset:19456
	s_mov_b32 m0, s47
	s_nop 0
	global_load_lds_dwordx4 v132, s[54:55]
	ds_read_b128 v[202:205], v143 offset:20480
	s_mov_b32 m0, s48
	s_nop 0
	global_load_lds_dwordx4 v136, s[54:55]
	ds_read_b128 v[206:209], v143 offset:21504
	s_add_u32 s58, s22, s4
	s_addc_u32 s59, s23, s5
	s_mov_b32 m0, s28
	s_nop 0
	global_load_lds_dwordx4 v130, s[22:23]
	ds_read_b128 v[210:213], v143 offset:22528
	s_mov_b32 m0, s29
	s_nop 0
	global_load_lds_dwordx4 v134, s[22:23]
	ds_read_b128 v[214:217], v143 offset:23552
	s_waitcnt lgkmcnt(0)
	s_barrier
	s_setprio 1
	s_waitcnt lgkmcnt(0)
	v_mfma_f32_16x16x32_bf16 v[94:97], v[146:149], v[186:189], v[94:97]
	v_mfma_f32_16x16x32_bf16 v[86:89], v[154:157], v[186:189], v[86:89]
	v_mfma_f32_16x16x32_bf16 v[102:105], v[146:149], v[194:197], v[102:105]
	v_mfma_f32_16x16x32_bf16 v[98:101], v[154:157], v[194:197], v[98:101]
	v_mfma_f32_16x16x32_bf16 v[110:113], v[146:149], v[202:205], v[110:113]
	v_mfma_f32_16x16x32_bf16 v[106:109], v[154:157], v[202:205], v[106:109]
	v_mfma_f32_16x16x32_bf16 v[126:129], v[146:149], v[210:213], v[126:129]
	v_mfma_f32_16x16x32_bf16 v[122:125], v[154:157], v[210:213], v[122:125]
	v_mfma_f32_16x16x32_bf16 v[94:97], v[150:153], v[190:193], v[94:97]
	v_mfma_f32_16x16x32_bf16 v[86:89], v[158:161], v[190:193], v[86:89]
	v_mfma_f32_16x16x32_bf16 v[102:105], v[150:153], v[198:201], v[102:105]
	v_mfma_f32_16x16x32_bf16 v[98:101], v[158:161], v[198:201], v[98:101]
	v_mfma_f32_16x16x32_bf16 v[110:113], v[150:153], v[206:209], v[110:113]
	v_mfma_f32_16x16x32_bf16 v[106:109], v[158:161], v[206:209], v[106:109]
	v_mfma_f32_16x16x32_bf16 v[126:129], v[150:153], v[214:217], v[126:129]
	v_mfma_f32_16x16x32_bf16 v[122:125], v[158:161], v[214:217], v[122:125]
	s_setprio 0
	s_setprio 1
	v_mfma_f32_16x16x32_bf16 v[58:61], v[162:165], v[186:189], v[58:61]
	v_mfma_f32_16x16x32_bf16 v[46:49], v[170:173], v[186:189], v[46:49]
	v_mfma_f32_16x16x32_bf16 v[74:77], v[162:165], v[194:197], v[74:77]
	v_mfma_f32_16x16x32_bf16 v[66:69], v[170:173], v[194:197], v[66:69]
	v_mfma_f32_16x16x32_bf16 v[90:93], v[162:165], v[202:205], v[90:93]
	v_mfma_f32_16x16x32_bf16 v[82:85], v[170:173], v[202:205], v[82:85]
	v_mfma_f32_16x16x32_bf16 v[118:121], v[162:165], v[210:213], v[118:121]
	v_mfma_f32_16x16x32_bf16 v[114:117], v[170:173], v[210:213], v[114:117]
	v_mfma_f32_16x16x32_bf16 v[58:61], v[166:169], v[190:193], v[58:61]
	v_mfma_f32_16x16x32_bf16 v[46:49], v[174:177], v[190:193], v[46:49]
	v_mfma_f32_16x16x32_bf16 v[74:77], v[166:169], v[198:201], v[74:77]
	v_mfma_f32_16x16x32_bf16 v[66:69], v[174:177], v[198:201], v[66:69]
	v_mfma_f32_16x16x32_bf16 v[90:93], v[166:169], v[206:209], v[90:93]
	v_mfma_f32_16x16x32_bf16 v[82:85], v[174:177], v[206:209], v[82:85]
	v_mfma_f32_16x16x32_bf16 v[118:121], v[166:169], v[214:217], v[118:121]
	v_mfma_f32_16x16x32_bf16 v[114:117], v[174:177], v[214:217], v[114:117]
	s_setprio 0
	s_waitcnt vmcnt(8)
	s_barrier
; #define PG8_STAGE(bufoff, gbase, voff) do { _Pragma("unroll") for (int _i = 0; _i < 2; ++_i) \
;         __builtin_amdgcn_global_load_lds((const unsigned*)((const char*)(gbase) + (voff)[_i]), (LAS unsigned*)(lds + (bufoff) + ldsw + _i * 8192), 16, 0, 0); } while (0)
; #define PG8_LDA(dst, b, h) do { _Pragma("unroll") for (int m = 0; m < 4; ++m) _Pragma("unroll") for (int k = 0; k < 2; ++k) dst[m][k] = *(const LAS bf16x8*)(lds + PG8_SA(b, h) + aoff + m * 2048 + k * 1024); } while (0)
; #define PG8_LDB(dst, b, h) do { _Pragma("unroll") for (int n = 0; n < 2; ++n) _Pragma("unroll") for (int k = 0; k < 2; ++k) dst[n][k] = *(const LAS bf16x8*)(lds + PG8_SB(b, h) + boff + n * 2048 + k * 1024); } while (0)
; #define PG8_MMA(ai, bj, At, Bt) do { __builtin_amdgcn_s_setprio(1); _Pragma("unroll") for (int m = 0; m < 4; ++m) _Pragma("unroll") for (int n = 0; n < 2; ++n) _Pragma("unroll") for (int k = 0; k < 2; ++k) \
;         acc[ai][bj][m][n] = __builtin_amdgcn_mfma_f32_16x16x32_bf16(Bt[n][k], At[m][k], acc[ai][bj][m][n], 0, 0, 0); __builtin_amdgcn_s_setprio(0); } while (0)
; #define PG8_WAIT_V(n) asm volatile("s_waitcnt vmcnt(" #n ")" ::: "memory")
; #define PG8_WAIT_L(n) asm volatile("s_waitcnt lgkmcnt(" #n ")" ::: "memory")
; #define PG8_BAR __builtin_amdgcn_s_barrier()
; #define PG8_SCHED __builtin_amdgcn_sched_barrier(0)
; template <class Epi, class Sched, bool ALIGN_EPI, class Hook = NoHook>
; __device__ __forceinline__ void gemm_phase(LAS unsigned char* lds, const Gemm g, const Sched& S, const Epi& E, const Hook& H = Hook()) {
;     ...
;             PG8_LDB(B0, 1, 0); PG8_LDB(B1, 1, 1); PG8_SCHED; PG8_LDA(At, 1, 0); PG8_STAGE(PG8_SA(0, 1), a2 + hA, voffA);
;             PG8_WAIT_V(8); PG8_WAIT_L(0); PG8_BAR; PG8_MMA(0, 0, At, B0); PG8_MMA(0, 1, At, B1); PG8_BAR; PG8_SCHED;
;             PG8_LDA(At, 1, 1); PG8_STAGE(PG8_SB(1, 0), b3, voffB); PG8_STAGE(PG8_SB(1, 1), b3 + hB, voffB); PG8_STAGE(PG8_SA(1, 0), a3, voffA);
;             PG8_WAIT_V(8); PG8_WAIT_L(0); PG8_BAR; PG8_MMA(1, 0, At, B0); PG8_MMA(1, 1, At, B1); PG8_BAR; PG8_SCHED;
;         }
	ds_read_b128 v[146:149], v144
	ds_read_b128 v[150:153], v144 offset:1024
	s_add_u32 s22, s22, 0x100000
	s_addc_u32 s23, s23, 0
	s_mov_b32 m0, s38
	s_nop 0
	global_load_lds_dwordx4 v130, s[22:23]
	ds_read_b128 v[154:157], v144 offset:2048
	ds_read_b128 v[158:161], v144 offset:3072
	ds_read_b128 v[162:165], v145
	ds_read_b128 v[166:169], v145 offset:1024
	ds_read_b128 v[170:173], v145 offset:2048
	ds_read_b128 v[174:177], v145 offset:3072
	ds_read_b128 v[186:189], v143 offset:32768
	s_mov_b32 m0, s39
	s_nop 0
	global_load_lds_dwordx4 v134, s[22:23]
	ds_read_b128 v[190:193], v143 offset:33792
	ds_read_b128 v[194:197], v143 offset:34816
	ds_read_b128 v[198:201], v143 offset:35840
	ds_read_b128 v[202:205], v143 offset:36864
	ds_read_b128 v[206:209], v143 offset:37888
	ds_read_b128 v[210:213], v143 offset:38912
	ds_read_b128 v[214:217], v143 offset:39936
	s_waitcnt lgkmcnt(0)
	s_barrier
	s_setprio 1
	s_waitcnt lgkmcnt(0)
	v_mfma_f32_16x16x32_bf16 v[54:57], v[146:149], v[186:189], v[54:57]
	v_mfma_f32_16x16x32_bf16 v[34:37], v[154:157], v[186:189], v[34:37]
	v_mfma_f32_16x16x32_bf16 v[42:45], v[146:149], v[194:197], v[42:45]
	v_mfma_f32_16x16x32_bf16 v[30:33], v[154:157], v[194:197], v[30:33]
	v_mfma_f32_16x16x32_bf16 v[62:65], v[146:149], v[202:205], v[62:65]
	v_mfma_f32_16x16x32_bf16 v[50:53], v[154:157], v[202:205], v[50:53]
	v_mfma_f32_16x16x32_bf16 v[78:81], v[146:149], v[210:213], v[78:81]
	v_mfma_f32_16x16x32_bf16 v[70:73], v[154:157], v[210:213], v[70:73]
	v_mfma_f32_16x16x32_bf16 v[54:57], v[150:153], v[190:193], v[54:57]
	v_mfma_f32_16x16x32_bf16 v[34:37], v[158:161], v[190:193], v[34:37]
	v_mfma_f32_16x16x32_bf16 v[42:45], v[150:153], v[198:201], v[42:45]
	v_mfma_f32_16x16x32_bf16 v[30:33], v[158:161], v[198:201], v[30:33]
	v_mfma_f32_16x16x32_bf16 v[62:65], v[150:153], v[206:209], v[62:65]
	v_mfma_f32_16x16x32_bf16 v[50:53], v[158:161], v[206:209], v[50:53]
	v_mfma_f32_16x16x32_bf16 v[78:81], v[150:153], v[214:217], v[78:81]
	v_mfma_f32_16x16x32_bf16 v[70:73], v[158:161], v[214:217], v[70:73]
	s_setprio 0
	s_setprio 1
	v_mfma_f32_16x16x32_bf16 v[10:13], v[162:165], v[186:189], v[10:13]
	v_mfma_f32_16x16x32_bf16 v[2:5], v[170:173], v[186:189], v[2:5]
	v_mfma_f32_16x16x32_bf16 v[14:17], v[162:165], v[194:197], v[14:17]
	v_mfma_f32_16x16x32_bf16 v[6:9], v[170:173], v[194:197], v[6:9]
	v_mfma_f32_16x16x32_bf16 v[22:25], v[162:165], v[202:205], v[22:25]
	v_mfma_f32_16x16x32_bf16 v[18:21], v[170:173], v[202:205], v[18:21]
	v_mfma_f32_16x16x32_bf16 v[38:41], v[162:165], v[210:213], v[38:41]
	v_mfma_f32_16x16x32_bf16 v[26:29], v[170:173], v[210:213], v[26:29]
	v_mfma_f32_16x16x32_bf16 v[10:13], v[166:169], v[190:193], v[10:13]
	v_mfma_f32_16x16x32_bf16 v[2:5], v[174:177], v[190:193], v[2:5]
	v_mfma_f32_16x16x32_bf16 v[14:17], v[166:169], v[198:201], v[14:17]
	v_mfma_f32_16x16x32_bf16 v[6:9], v[174:177], v[198:201], v[6:9]
	v_mfma_f32_16x16x32_bf16 v[22:25], v[166:169], v[206:209], v[22:25]
	v_mfma_f32_16x16x32_bf16 v[18:21], v[174:177], v[206:209], v[18:21]
	v_mfma_f32_16x16x32_bf16 v[38:41], v[166:169], v[214:217], v[38:41]
	v_mfma_f32_16x16x32_bf16 v[26:29], v[174:177], v[214:217], v[26:29]
	s_setprio 0
	s_waitcnt vmcnt(8)
	s_barrier
	s_mov_b32 m0, s49
	s_add_u32 s56, s20, s4
	s_addc_u32 s57, s21, s5
	s_add_u32 s20, s20, 0x100080
	ds_read_b128 v[186:189], v143 offset:49152
	ds_read_b128 v[190:193], v143 offset:50176
	global_load_lds_dwordx4 v132, s[56:57]
	ds_read_b128 v[194:197], v143 offset:51200
	s_mov_b32 m0, s50
	s_addc_u32 s21, s21, 0
	global_load_lds_dwordx4 v136, s[56:57]
	ds_read_b128 v[198:201], v143 offset:52224
	s_mov_b32 m0, s51
	s_nop 0
	global_load_lds_dwordx4 v132, s[20:21]
	ds_read_b128 v[202:205], v143 offset:53248
	s_mov_b32 m0, s52
	s_nop 0
	global_load_lds_dwordx4 v136, s[20:21]
	ds_read_b128 v[206:209], v143 offset:54272
	s_mov_b32 m0, s40
	s_nop 0
	global_load_lds_dwordx4 v130, s[58:59]
	ds_read_b128 v[210:213], v143 offset:55296
	s_mov_b32 m0, s41
	s_nop 0
	global_load_lds_dwordx4 v134, s[58:59]
	ds_read_b128 v[214:217], v143 offset:56320
	s_waitcnt lgkmcnt(0)
	s_barrier
	s_setprio 1
	s_waitcnt lgkmcnt(0)
	v_mfma_f32_16x16x32_bf16 v[94:97], v[146:149], v[186:189], v[94:97]
	v_mfma_f32_16x16x32_bf16 v[86:89], v[154:157], v[186:189], v[86:89]
	v_mfma_f32_16x16x32_bf16 v[102:105], v[146:149], v[194:197], v[102:105]
	v_mfma_f32_16x16x32_bf16 v[98:101], v[154:157], v[194:197], v[98:101]
	v_mfma_f32_16x16x32_bf16 v[110:113], v[146:149], v[202:205], v[110:113]
	v_mfma_f32_16x16x32_bf16 v[106:109], v[154:157], v[202:205], v[106:109]
	v_mfma_f32_16x16x32_bf16 v[126:129], v[146:149], v[210:213], v[126:129]
	v_mfma_f32_16x16x32_bf16 v[122:125], v[154:157], v[210:213], v[122:125]
	v_mfma_f32_16x16x32_bf16 v[94:97], v[150:153], v[190:193], v[94:97]
	v_mfma_f32_16x16x32_bf16 v[86:89], v[158:161], v[190:193], v[86:89]
	v_mfma_f32_16x16x32_bf16 v[102:105], v[150:153], v[198:201], v[102:105]
	v_mfma_f32_16x16x32_bf16 v[98:101], v[158:161], v[198:201], v[98:101]
	v_mfma_f32_16x16x32_bf16 v[110:113], v[150:153], v[206:209], v[110:113]
	v_mfma_f32_16x16x32_bf16 v[106:109], v[158:161], v[206:209], v[106:109]
	v_mfma_f32_16x16x32_bf16 v[126:129], v[150:153], v[214:217], v[126:129]
	v_mfma_f32_16x16x32_bf16 v[122:125], v[158:161], v[214:217], v[122:125]
	s_setprio 0
	s_setprio 1
	v_mfma_f32_16x16x32_bf16 v[58:61], v[162:165], v[186:189], v[58:61]
	v_mfma_f32_16x16x32_bf16 v[46:49], v[170:173], v[186:189], v[46:49]
	v_mfma_f32_16x16x32_bf16 v[74:77], v[162:165], v[194:197], v[74:77]
	v_mfma_f32_16x16x32_bf16 v[66:69], v[170:173], v[194:197], v[66:69]
	v_mfma_f32_16x16x32_bf16 v[90:93], v[162:165], v[202:205], v[90:93]
	v_mfma_f32_16x16x32_bf16 v[82:85], v[170:173], v[202:205], v[82:85]
	v_mfma_f32_16x16x32_bf16 v[118:121], v[162:165], v[210:213], v[118:121]
	v_mfma_f32_16x16x32_bf16 v[114:117], v[170:173], v[210:213], v[114:117]
	v_mfma_f32_16x16x32_bf16 v[58:61], v[166:169], v[190:193], v[58:61]
	v_mfma_f32_16x16x32_bf16 v[46:49], v[174:177], v[190:193], v[46:49]
	v_mfma_f32_16x16x32_bf16 v[74:77], v[166:169], v[198:201], v[74:77]
	v_mfma_f32_16x16x32_bf16 v[66:69], v[174:177], v[198:201], v[66:69]
	v_mfma_f32_16x16x32_bf16 v[90:93], v[166:169], v[206:209], v[90:93]
	v_mfma_f32_16x16x32_bf16 v[82:85], v[174:177], v[206:209], v[82:85]
	v_mfma_f32_16x16x32_bf16 v[118:121], v[166:169], v[214:217], v[118:121]
	v_mfma_f32_16x16x32_bf16 v[114:117], v[174:177], v[214:217], v[114:117]
	s_setprio 0
	s_waitcnt vmcnt(8)
	s_barrier
	s_add_i32 s42, s42, 2
	s_add_u32 s6, s6, 0x100
	s_addc_u32 s7, s7, 0
	s_cmp_gt_u32 s42, 61
	s_cbranch_scc0 .LBB0_850
	s_branch .Lmy_d850X

; #define PG8_BAR __builtin_amdgcn_s_barrier()
; template <class Epi, class Sched, bool ALIGN_EPI, class Hook = NoHook>
; __device__ __forceinline__ void gemm_phase(LAS unsigned char* lds, const Gemm g, const Sched& S, const Epi& E, const Hook& H = Hook()) {
;     ...
;         if constexpr (ALIGN_EPI) { if (wr == 0) PG8_BAR; }
.Lmy_d850X:
	s_cmpk_lt_u32 s26, 0x100
	s_cbranch_scc0 .LBB0_853
	s_barrier

;     __host__ __device__ bool next(int i, Unit& u) const { const bool ok = StaticOrder::next(i >> 1, u); if (i & 1) { u.ka = D_INNER; u.nkt = D_ATT / BK; } else { u.ka = 0; u.nkt = D_INNER / BK; } return ok; }
;     __host__ __device__ bool next(int i, Unit& u) const { const long L = (long)i * G + c; if (L >= (long)nM * nS) return false; u.pm = (int)(L % nM); u.pn = 0; u.ka = (int)(L / nM) * kslab; u.nkt = kslab / BK; return true; }
;     __host__ __device__ bool next(int i, Unit& u) const { if (i > 0) return false; const int x = c & 7, j = c >> 3; u.pm = 16 * s + 4 * (x >> 1) + (j & 3); u.pn = 8 * (x & 1) + (j >> 2); u.ka = 0; u.nkt = nkt; return true; }
; #define PG8_STAGE(bufoff, gbase, voff) do { _Pragma("unroll") for (int _i = 0; _i < 2; ++_i) \
;         __builtin_amdgcn_global_load_lds((const unsigned*)((const char*)(gbase) + (voff)[_i]), (LAS unsigned*)(lds + (bufoff) + ldsw + _i * 8192), 16, 0, 0); } while (0)
; #define PG8_WAIT_V(n) asm volatile("s_waitcnt vmcnt(" #n ")" ::: "memory")
; template <class Epi, class Sched, bool ALIGN_EPI, class Hook = NoHook>
; __device__ __forceinline__ void gemm_phase(LAS unsigned char* lds, const Gemm g, const Sched& S, const Epi& E, const Hook& H = Hook()) {
;     ...
;     const int aoff = lds_byte(wr * 64 + fr, fq * 8), boff = lds_byte(wc * 32 + fr, fq * 8);
;     ...
;     Unit cur, nxt; int ui = 0;
;     if (!S.next(0, cur)) return;
;     f32x4 acc[2][2][4][2];
; #pragma unroll
;     for (int a = 0; a < 2; ++a)
; #pragma unroll
;         for (int b = 0; b < 2; ++b)
; #pragma unroll
;             for (int m = 0; m < 4; ++m)
; #pragma unroll
;                 for (int n = 0; n < 2; ++n) acc[a][b][m][n] = (f32x4){0.f, 0.f, 0.f, 0.f};
;     bf16x8 At[4][2], B0[2][2], B1[2][2];
;     const char* cA = (const char*)g.A + (size_t)cur.pm * tA + (size_t)cur.ka * 2; const char* cB = (const char*)g.Bt + (size_t)cur.pn * 2 * hB + (size_t)cur.ka * 2;
;     S.a_ready(cur);
;     if constexpr (Hook::ON) H.unit_start(cur);
;     PG8_STAGE(PG8_SB(0, 0), cB, voffB); PG8_STAGE(PG8_SB(0, 1), cB + hB, voffB); PG8_STAGE(PG8_SA(0, 0), cA, voffA); PG8_STAGE(PG8_SA(0, 1), cA + hA, voffA);
;     if (wr == 1) PG8_BAR;
;     PG8_WAIT_V(2); PG8_BAR;
;     PG8_STAGE(PG8_SB(1, 0), cB + kstep, voffB); PG8_STAGE(PG8_SA(1, 0), cA + kstep, voffA); PG8_STAGE(PG8_SB(1, 1), cB + hB + kstep, voffB);
;     PG8_WAIT_V(6); PG8_BAR;
.LBB0_895:
	v_and_b32_e32 v183, 15, v182
	v_and_b32_e32 v16, 48, v182
	v_lshlrev_b32_e32 v17, 2, v182
	s_and_b32 s25, s23, 3
	s_lshl_b32 s4, s24, 13
	v_lshl_or_b32 v16, v183, 6, v16
	v_and_b32_e32 v17, 32, v17
	v_bitop3_b32 v18, v16, s4, v17 bitop3:0xde
	s_lshl_b32 s4, s25, 12
	v_bitop3_b32 v16, v16, s4, v17 bitop3:0xde
	s_mov_b64 s[4:5], 0x80
	s_add_i32 m0, s27, 0x18000
	v_lshl_add_u64 v[8:9], v[8:9], 0, s[4:5]
	s_waitcnt vmcnt(2)
	s_barrier
	global_load_lds_dwordx4 v[8:9], off
	v_lshl_add_u64 v[6:7], v[6:7], 0, s[4:5]
	s_add_i32 m0, s27, 0x1a000
	s_add_i32 s40, s27, 0x8000
	global_load_lds_dwordx4 v[6:7], off
	v_lshl_add_u64 v[4:5], v[4:5], 0, s[4:5]
	s_mov_b32 m0, s40
	s_add_i32 s41, s27, 0xa000
	global_load_lds_dwordx4 v[4:5], off
	v_lshl_add_u64 v[2:3], v[2:3], 0, s[4:5]
	s_mov_b32 m0, s41
	s_add_i32 s31, s31, s33
	global_load_lds_dwordx4 v[2:3], off
	s_add_i32 m0, s27, 0x1c000
	v_lshl_add_u64 v[2:3], s[18:19], 0, v[180:181]
	global_load_lds_dwordx4 v[2:3], off
	v_lshl_add_u64 v[2:3], s[18:19], 0, v[134:135]
	s_add_i32 m0, s27, 0x1e000
	s_lshl_b32 s6, s31, 21
	global_load_lds_dwordx4 v[2:3], off
	v_lshlrev_b32_e32 v2, 16, v10
	v_and_b32_e32 v2, 0xfffe0000, v2
	s_add_i32 s6, s6, 0x2000000
	v_lshl_add_u32 v2, v11, 13, v2
	v_and_b32_e32 v3, 1, v10
	v_lshl_or_b32 v2, v3, 6, v2
	s_add_u32 s6, s96, s6
	v_lshl_add_u32 v2, v12, 1, v2
	v_mov_b32_e32 v3, v181
	s_addc_u32 s7, s97, 0
	v_lshl_add_u64 v[136:137], s[6:7], 0, v[2:3]
	v_lshlrev_b32_e32 v2, 16, v13
	v_and_b32_e32 v2, 0xfffe0000, v2
	v_lshl_add_u32 v2, v14, 13, v2
	v_and_b32_e32 v3, 1, v13
	s_waitcnt vmcnt(6)
	v_lshl_or_b32 v2, v3, 6, v2
	v_lshl_add_u32 v2, v15, 1, v2
	v_mov_b32_e32 v3, v181
	v_add_u32_e32 v141, s35, v16
	s_add_i32 s33, s34, s44
	s_add_i32 s35, s35, s44
	v_add_u32_e32 v143, s36, v16
	v_add_u32_e32 v144, s37, v16
	s_add_i32 s36, s36, s44
	s_add_i32 s37, s37, s44
	v_lshl_or_b32 v185, s24, 6, v183
	v_lshl_add_u64 v[138:139], s[6:7], 0, v[2:3]
	s_mov_b32 s18, -2
	s_mov_b64 s[6:7], 0x78400080
	v_add_u32_e32 v140, s34, v16
	v_add_u32_e32 v142, 0, v18
	s_add_i32 s19, s27, 0xc000
	s_add_i32 s31, s27, 0xe000
	s_add_i32 s34, s33, 0x2000
	s_add_i32 s42, s35, 0x2000
	s_add_i32 s43, s36, 0x2000
	s_add_i32 s44, s37, 0x2000
	v_mov_b32_e32 v114, v181
	v_mov_b32_e32 v115, v181
	v_mov_b32_e32 v116, v181
	v_mov_b32_e32 v117, v181
	v_mov_b32_e32 v118, v181
	v_mov_b32_e32 v119, v181
	v_mov_b32_e32 v120, v181
	v_mov_b32_e32 v121, v181
	v_mov_b32_e32 v82, v181
	v_mov_b32_e32 v83, v181
	v_mov_b32_e32 v84, v181
	v_mov_b32_e32 v85, v181
	v_mov_b32_e32 v90, v181
	v_mov_b32_e32 v91, v181
	v_mov_b32_e32 v92, v181
	v_mov_b32_e32 v93, v181
	v_mov_b32_e32 v66, v181
	v_mov_b32_e32 v67, v181
	v_mov_b32_e32 v68, v181
	v_mov_b32_e32 v69, v181
	v_mov_b32_e32 v74, v181
	v_mov_b32_e32 v75, v181
	v_mov_b32_e32 v76, v181
	v_mov_b32_e32 v77, v181
	v_mov_b32_e32 v46, v181
	v_mov_b32_e32 v47, v181
	v_mov_b32_e32 v48, v181
	v_mov_b32_e32 v49, v181
	v_mov_b32_e32 v58, v181
	v_mov_b32_e32 v59, v181
	v_mov_b32_e32 v60, v181
	v_mov_b32_e32 v61, v181
	v_mov_b32_e32 v122, v181
	v_mov_b32_e32 v123, v181
	v_mov_b32_e32 v124, v181
	v_mov_b32_e32 v125, v181
	v_mov_b32_e32 v126, v181
	v_mov_b32_e32 v127, v181
	v_mov_b32_e32 v128, v181
	v_mov_b32_e32 v129, v181
	v_mov_b32_e32 v106, v181
	v_mov_b32_e32 v107, v181
	v_mov_b32_e32 v108, v181
	v_mov_b32_e32 v109, v181
	v_mov_b32_e32 v110, v181
	v_mov_b32_e32 v111, v181
	v_mov_b32_e32 v112, v181
	v_mov_b32_e32 v113, v181
	v_mov_b32_e32 v98, v181
	v_mov_b32_e32 v99, v181
	v_mov_b32_e32 v100, v181
	v_mov_b32_e32 v101, v181
	v_mov_b32_e32 v102, v181
	v_mov_b32_e32 v103, v181
	v_mov_b32_e32 v104, v181
	v_mov_b32_e32 v105, v181
	v_mov_b32_e32 v86, v181
	v_mov_b32_e32 v87, v181
	v_mov_b32_e32 v88, v181
	v_mov_b32_e32 v89, v181
	v_mov_b32_e32 v94, v181
	v_mov_b32_e32 v95, v181
	v_mov_b32_e32 v96, v181
	v_mov_b32_e32 v97, v181
	v_mov_b32_e32 v26, v181
	v_mov_b32_e32 v27, v181
	v_mov_b32_e32 v28, v181
	v_mov_b32_e32 v29, v181
	v_mov_b32_e32 v38, v181
	v_mov_b32_e32 v39, v181
	v_mov_b32_e32 v40, v181
	v_mov_b32_e32 v41, v181
	v_mov_b32_e32 v18, v181
	v_mov_b32_e32 v19, v181
	v_mov_b32_e32 v20, v181
	v_mov_b32_e32 v21, v181
	v_mov_b32_e32 v22, v181
	v_mov_b32_e32 v23, v181
	v_mov_b32_e32 v24, v181
	v_mov_b32_e32 v25, v181
	v_mov_b32_e32 v6, v181
	v_mov_b32_e32 v7, v181
	v_mov_b32_e32 v8, v181
	v_mov_b32_e32 v9, v181
	v_mov_b32_e32 v14, v181
	v_mov_b32_e32 v15, v181
	v_mov_b32_e32 v16, v181
	v_mov_b32_e32 v17, v181
	v_mov_b32_e32 v2, v181
	v_mov_b32_e32 v4, v181
	v_mov_b32_e32 v5, v181
	v_mov_b32_e32 v10, v181
	v_mov_b32_e32 v11, v181
	v_mov_b32_e32 v12, v181
	v_mov_b32_e32 v13, v181
	v_mov_b32_e32 v70, v181
	v_mov_b32_e32 v71, v181
	v_mov_b32_e32 v72, v181
	v_mov_b32_e32 v73, v181
	v_mov_b32_e32 v78, v181
	v_mov_b32_e32 v79, v181
	v_mov_b32_e32 v80, v181
	v_mov_b32_e32 v81, v181
	v_mov_b32_e32 v50, v181
	v_mov_b32_e32 v51, v181
	v_mov_b32_e32 v52, v181
	v_mov_b32_e32 v53, v181
	v_mov_b32_e32 v62, v181
	v_mov_b32_e32 v63, v181
	v_mov_b32_e32 v64, v181
	v_mov_b32_e32 v65, v181
	v_mov_b32_e32 v30, v181
	v_mov_b32_e32 v31, v181
	v_mov_b32_e32 v32, v181
	v_mov_b32_e32 v33, v181
	v_mov_b32_e32 v42, v181
	v_mov_b32_e32 v43, v181
	v_mov_b32_e32 v44, v181
	v_mov_b32_e32 v45, v181
	v_mov_b32_e32 v34, v181
	v_mov_b32_e32 v35, v181
	v_mov_b32_e32 v36, v181
	v_mov_b32_e32 v37, v181
	v_mov_b32_e32 v54, v181
	v_mov_b32_e32 v55, v181
	v_mov_b32_e32 v56, v181
	v_mov_b32_e32 v57, v181
	s_barrier
	s_cmpk_lt_u32 s22, 0x100
	s_cbranch_scc0 .Lmy_d896B
; #define PG8_STAGE(bufoff, gbase, voff) do { _Pragma("unroll") for (int _i = 0; _i < 2; ++_i) \
;         __builtin_amdgcn_global_load_lds((const unsigned*)((const char*)(gbase) + (voff)[_i]), (LAS unsigned*)(lds + (bufoff) + ldsw + _i * 8192), 16, 0, 0); } while (0)
; #define PG8_LDA(dst, b, h) do { _Pragma("unroll") for (int m = 0; m < 4; ++m) _Pragma("unroll") for (int k = 0; k < 2; ++k) dst[m][k] = *(const LAS bf16x8*)(lds + PG8_SA(b, h) + aoff + m * 2048 + k * 1024); } while (0)
; #define PG8_LDB(dst, b, h) do { _Pragma("unroll") for (int n = 0; n < 2; ++n) _Pragma("unroll") for (int k = 0; k < 2; ++k) dst[n][k] = *(const LAS bf16x8*)(lds + PG8_SB(b, h) + boff + n * 2048 + k * 1024); } while (0)
; #define PG8_MMA(ai, bj, At, Bt) do { __builtin_amdgcn_s_setprio(1); _Pragma("unroll") for (int m = 0; m < 4; ++m) _Pragma("unroll") for (int n = 0; n < 2; ++n) _Pragma("unroll") for (int k = 0; k < 2; ++k) \
;         acc[ai][bj][m][n] = __builtin_amdgcn_mfma_f32_16x16x32_bf16(Bt[n][k], At[m][k], acc[ai][bj][m][n], 0, 0, 0); __builtin_amdgcn_s_setprio(0); } while (0)
; #define PG8_WAIT_V(n) asm volatile("s_waitcnt vmcnt(" #n ")" ::: "memory")
; #define PG8_WAIT_L(n) asm volatile("s_waitcnt lgkmcnt(" #n ")" ::: "memory")
; #define PG8_BAR __builtin_amdgcn_s_barrier()
; template <class Epi, class Sched, bool ALIGN_EPI, class Hook = NoHook>
; __device__ __forceinline__ void gemm_phase(LAS unsigned char* lds, const Gemm g, const Sched& S, const Epi& E, const Hook& H = Hook()) {
;     ...
;             const bool last = (t == nt - 2);
;             const char* a1 = cA + (size_t)(t + 1) * kstep;
;             const char* a2 = last ? nA : cA + (size_t)(t + 2) * kstep; const char* b2 = last ? nB : cB + (size_t)(t + 2) * kstep;
;             const char* a3 = a2 + kstep; const char* b3 = b2 + kstep;
;             if (last && has_next) S.a_ready(nxt);
;             PG8_LDB(B0, 0, 0); PG8_LDB(B1, 0, 1); PG8_SCHED; PG8_LDA(At, 0, 0); PG8_STAGE(PG8_SA(1, 1), a1 + hA, voffA);
;             PG8_WAIT_V(8); PG8_WAIT_L(0); PG8_BAR; PG8_MMA(0, 0, At, B0); PG8_MMA(0, 1, At, B1); PG8_BAR; PG8_SCHED;
;             PG8_LDA(At, 0, 1); PG8_STAGE(PG8_SB(0, 0), b2, voffB); PG8_STAGE(PG8_SB(0, 1), b2 + hB, voffB); PG8_STAGE(PG8_SA(0, 0), a2, voffA);
;             PG8_WAIT_V(8); PG8_WAIT_L(0); PG8_BAR; PG8_MMA(1, 0, At, B0); PG8_MMA(1, 1, At, B1); PG8_BAR; PG8_SCHED;
.LBB0_896:
	ds_read_b128 v[146:149], v140
	ds_read_b128 v[150:153], v140 offset:1024
	s_add_u32 s10, s6, 0x87c00080
	s_addc_u32 s11, s7, -1
	s_cmp_lg_u32 s18, 60
	s_cselect_b32 s10, s10, 0
	s_cselect_b32 s11, s11, 0
	s_add_u32 s16, s2, s10
	s_addc_u32 s17, s3, s11
	s_add_u32 s10, s14, s10
	s_addc_u32 s11, s15, s11
	s_mov_b32 m0, s19
	ds_read_b128 v[154:157], v140 offset:2048
	ds_read_b128 v[158:161], v140 offset:3072
	ds_read_b128 v[162:165], v141
	ds_read_b128 v[166:169], v141 offset:1024
	ds_read_b128 v[170:173], v141 offset:2048
	ds_read_b128 v[174:177], v141 offset:3072
	v_lshl_add_u64 v[178:179], v[136:137], 0, s[6:7]
	global_load_lds_dwordx4 v[178:179], off
	ds_read_b128 v[186:189], v142
	ds_read_b128 v[190:193], v142 offset:1024
	ds_read_b128 v[194:197], v142 offset:2048
	ds_read_b128 v[198:201], v142 offset:3072
	ds_read_b128 v[202:205], v142 offset:4096
	ds_read_b128 v[206:209], v142 offset:5120
	ds_read_b128 v[210:213], v142 offset:6144
	ds_read_b128 v[214:217], v142 offset:7168
	v_lshl_add_u64 v[178:179], v[138:139], 0, s[6:7]
	s_mov_b32 m0, s31
	s_nop 0
	global_load_lds_dwordx4 v[178:179], off
	s_waitcnt lgkmcnt(0)
	s_barrier
	s_setprio 1
	s_waitcnt lgkmcnt(0)
	v_mfma_f32_16x16x32_bf16 v[54:57], v[146:149], v[186:189], v[54:57]
	v_mfma_f32_16x16x32_bf16 v[34:37], v[154:157], v[186:189], v[34:37]
	v_mfma_f32_16x16x32_bf16 v[42:45], v[146:149], v[194:197], v[42:45]
	v_mfma_f32_16x16x32_bf16 v[30:33], v[154:157], v[194:197], v[30:33]
	v_mfma_f32_16x16x32_bf16 v[62:65], v[146:149], v[202:205], v[62:65]
	v_mfma_f32_16x16x32_bf16 v[50:53], v[154:157], v[202:205], v[50:53]
	v_mfma_f32_16x16x32_bf16 v[78:81], v[146:149], v[210:213], v[78:81]
	v_mfma_f32_16x16x32_bf16 v[70:73], v[154:157], v[210:213], v[70:73]
	v_mfma_f32_16x16x32_bf16 v[54:57], v[150:153], v[190:193], v[54:57]
	v_mfma_f32_16x16x32_bf16 v[34:37], v[158:161], v[190:193], v[34:37]
	v_mfma_f32_16x16x32_bf16 v[42:45], v[150:153], v[198:201], v[42:45]
	v_mfma_f32_16x16x32_bf16 v[30:33], v[158:161], v[198:201], v[30:33]
	v_mfma_f32_16x16x32_bf16 v[62:65], v[150:153], v[206:209], v[62:65]
	v_mfma_f32_16x16x32_bf16 v[50:53], v[158:161], v[206:209], v[50:53]
	v_mfma_f32_16x16x32_bf16 v[78:81], v[150:153], v[214:217], v[78:81]
	v_mfma_f32_16x16x32_bf16 v[70:73], v[158:161], v[214:217], v[70:73]
	s_setprio 0
	s_setprio 1
	v_mfma_f32_16x16x32_bf16 v[10:13], v[162:165], v[186:189], v[10:13]
	v_mfma_f32_16x16x32_bf16 v[2:5], v[170:173], v[186:189], v[2:5]
	v_mfma_f32_16x16x32_bf16 v[14:17], v[162:165], v[194:197], v[14:17]
	v_mfma_f32_16x16x32_bf16 v[6:9], v[170:173], v[194:197], v[6:9]
	v_mfma_f32_16x16x32_bf16 v[22:25], v[162:165], v[202:205], v[22:25]
	v_mfma_f32_16x16x32_bf16 v[18:21], v[170:173], v[202:205], v[18:21]
	v_mfma_f32_16x16x32_bf16 v[38:41], v[162:165], v[210:213], v[38:41]
	v_mfma_f32_16x16x32_bf16 v[26:29], v[170:173], v[210:213], v[26:29]
	v_mfma_f32_16x16x32_bf16 v[10:13], v[166:169], v[190:193], v[10:13]
	v_mfma_f32_16x16x32_bf16 v[2:5], v[174:177], v[190:193], v[2:5]
	v_mfma_f32_16x16x32_bf16 v[14:17], v[166:169], v[198:201], v[14:17]
	v_mfma_f32_16x16x32_bf16 v[6:9], v[174:177], v[198:201], v[6:9]
	v_mfma_f32_16x16x32_bf16 v[22:25], v[166:169], v[206:209], v[22:25]
	v_mfma_f32_16x16x32_bf16 v[18:21], v[174:177], v[206:209], v[18:21]
	v_mfma_f32_16x16x32_bf16 v[38:41], v[166:169], v[214:217], v[38:41]
	v_mfma_f32_16x16x32_bf16 v[26:29], v[174:177], v[214:217], v[26:29]
	s_setprio 0
	s_waitcnt vmcnt(8)
	s_barrier
	s_mov_b32 m0, s33
	s_add_u32 s46, s10, 0x100000
	ds_read_b128 v[186:189], v142 offset:16384
	ds_read_b128 v[190:193], v142 offset:17408
	global_load_lds_dwordx4 v180, s[10:11]
	ds_read_b128 v[194:197], v142 offset:18432
	s_mov_b32 m0, s34
	s_addc_u32 s47, s11, 0
	global_load_lds_dwordx4 v134, s[10:11]
	ds_read_b128 v[198:201], v142 offset:19456
	s_mov_b32 m0, s35
	s_nop 0
	global_load_lds_dwordx4 v180, s[46:47]
	ds_read_b128 v[202:205], v142 offset:20480
	s_mov_b32 m0, s42
	s_nop 0
	global_load_lds_dwordx4 v134, s[46:47]
	ds_read_b128 v[206:209], v142 offset:21504
	s_add_u32 s50, s16, s4
	s_addc_u32 s51, s17, s5
	s_mov_b32 m0, s27
	s_nop 0
	global_load_lds_dwordx4 v130, s[16:17]
	ds_read_b128 v[210:213], v142 offset:22528
	s_mov_b32 m0, s28
	s_nop 0
	global_load_lds_dwordx4 v132, s[16:17]
	ds_read_b128 v[214:217], v142 offset:23552
	s_waitcnt lgkmcnt(0)
	s_barrier
	s_setprio 1
	s_waitcnt lgkmcnt(0)
	v_mfma_f32_16x16x32_bf16 v[94:97], v[146:149], v[186:189], v[94:97]
	v_mfma_f32_16x16x32_bf16 v[86:89], v[154:157], v[186:189], v[86:89]
	v_mfma_f32_16x16x32_bf16 v[102:105], v[146:149], v[194:197], v[102:105]
	v_mfma_f32_16x16x32_bf16 v[98:101], v[154:157], v[194:197], v[98:101]
	v_mfma_f32_16x16x32_bf16 v[110:113], v[146:149], v[202:205], v[110:113]
	v_mfma_f32_16x16x32_bf16 v[106:109], v[154:157], v[202:205], v[106:109]
	v_mfma_f32_16x16x32_bf16 v[126:129], v[146:149], v[210:213], v[126:129]
	v_mfma_f32_16x16x32_bf16 v[122:125], v[154:157], v[210:213], v[122:125]
	v_mfma_f32_16x16x32_bf16 v[94:97], v[150:153], v[190:193], v[94:97]
	v_mfma_f32_16x16x32_bf16 v[86:89], v[158:161], v[190:193], v[86:89]
	v_mfma_f32_16x16x32_bf16 v[102:105], v[150:153], v[198:201], v[102:105]
	v_mfma_f32_16x16x32_bf16 v[98:101], v[158:161], v[198:201], v[98:101]
	v_mfma_f32_16x16x32_bf16 v[110:113], v[150:153], v[206:209], v[110:113]
	v_mfma_f32_16x16x32_bf16 v[106:109], v[158:161], v[206:209], v[106:109]
	v_mfma_f32_16x16x32_bf16 v[126:129], v[150:153], v[214:217], v[126:129]
	v_mfma_f32_16x16x32_bf16 v[122:125], v[158:161], v[214:217], v[122:125]
	s_setprio 0
	s_setprio 1
	v_mfma_f32_16x16x32_bf16 v[58:61], v[162:165], v[186:189], v[58:61]
	v_mfma_f32_16x16x32_bf16 v[46:49], v[170:173], v[186:189], v[46:49]
	v_mfma_f32_16x16x32_bf16 v[74:77], v[162:165], v[194:197], v[74:77]
	v_mfma_f32_16x16x32_bf16 v[66:69], v[170:173], v[194:197], v[66:69]
	v_mfma_f32_16x16x32_bf16 v[90:93], v[162:165], v[202:205], v[90:93]
	v_mfma_f32_16x16x32_bf16 v[82:85], v[170:173], v[202:205], v[82:85]
	v_mfma_f32_16x16x32_bf16 v[118:121], v[162:165], v[210:213], v[118:121]
	v_mfma_f32_16x16x32_bf16 v[114:117], v[170:173], v[210:213], v[114:117]
	v_mfma_f32_16x16x32_bf16 v[58:61], v[166:169], v[190:193], v[58:61]
	v_mfma_f32_16x16x32_bf16 v[46:49], v[174:177], v[190:193], v[46:49]
	v_mfma_f32_16x16x32_bf16 v[74:77], v[166:169], v[198:201], v[74:77]
	v_mfma_f32_16x16x32_bf16 v[66:69], v[174:177], v[198:201], v[66:69]
	v_mfma_f32_16x16x32_bf16 v[90:93], v[166:169], v[206:209], v[90:93]
	v_mfma_f32_16x16x32_bf16 v[82:85], v[174:177], v[206:209], v[82:85]
	v_mfma_f32_16x16x32_bf16 v[118:121], v[166:169], v[214:217], v[118:121]
	v_mfma_f32_16x16x32_bf16 v[114:117], v[174:177], v[214:217], v[114:117]
	s_setprio 0
	s_waitcnt vmcnt(8)
	s_barrier
; #define PG8_STAGE(bufoff, gbase, voff) do { _Pragma("unroll") for (int _i = 0; _i < 2; ++_i) \
;         __builtin_amdgcn_global_load_lds((const unsigned*)((const char*)(gbase) + (voff)[_i]), (LAS unsigned*)(lds + (bufoff) + ldsw + _i * 8192), 16, 0, 0); } while (0)
; #define PG8_LDA(dst, b, h) do { _Pragma("unroll") for (int m = 0; m < 4; ++m) _Pragma("unroll") for (int k = 0; k < 2; ++k) dst[m][k] = *(const LAS bf16x8*)(lds + PG8_SA(b, h) + aoff + m * 2048 + k * 1024); } while (0)
; #define PG8_LDB(dst, b, h) do { _Pragma("unroll") for (int n = 0; n < 2; ++n) _Pragma("unroll") for (int k = 0; k < 2; ++k) dst[n][k] = *(const LAS bf16x8*)(lds + PG8_SB(b, h) + boff + n * 2048 + k * 1024); } while (0)
; #define PG8_MMA(ai, bj, At, Bt) do { __builtin_amdgcn_s_setprio(1); _Pragma("unroll") for (int m = 0; m < 4; ++m) _Pragma("unroll") for (int n = 0; n < 2; ++n) _Pragma("unroll") for (int k = 0; k < 2; ++k) \
;         acc[ai][bj][m][n] = __builtin_amdgcn_mfma_f32_16x16x32_bf16(Bt[n][k], At[m][k], acc[ai][bj][m][n], 0, 0, 0); __builtin_amdgcn_s_setprio(0); } while (0)
; #define PG8_WAIT_V(n) asm volatile("s_waitcnt vmcnt(" #n ")" ::: "memory")
; #define PG8_WAIT_L(n) asm volatile("s_waitcnt lgkmcnt(" #n ")" ::: "memory")
; #define PG8_BAR __builtin_amdgcn_s_barrier()
; #define PG8_SCHED __builtin_amdgcn_sched_barrier(0)
; template <class Epi, class Sched, bool ALIGN_EPI, class Hook = NoHook>
; __device__ __forceinline__ void gemm_phase(LAS unsigned char* lds, const Gemm g, const Sched& S, const Epi& E, const Hook& H = Hook()) {
;     ...
;             PG8_LDB(B0, 1, 0); PG8_LDB(B1, 1, 1); PG8_SCHED; PG8_LDA(At, 1, 0); PG8_STAGE(PG8_SA(0, 1), a2 + hA, voffA);
;             PG8_WAIT_V(8); PG8_WAIT_L(0); PG8_BAR; PG8_MMA(0, 0, At, B0); PG8_MMA(0, 1, At, B1); PG8_BAR; PG8_SCHED;
;             PG8_LDA(At, 1, 1); PG8_STAGE(PG8_SB(1, 0), b3, voffB); PG8_STAGE(PG8_SB(1, 1), b3 + hB, voffB); PG8_STAGE(PG8_SA(1, 0), a3, voffA);
;             PG8_WAIT_V(8); PG8_WAIT_L(0); PG8_BAR; PG8_MMA(1, 0, At, B0); PG8_MMA(1, 1, At, B1); PG8_BAR; PG8_SCHED;
;         }
	ds_read_b128 v[146:149], v143
	ds_read_b128 v[150:153], v143 offset:1024
	s_add_u32 s16, s16, 0x100000
	s_addc_u32 s17, s17, 0
	s_mov_b32 m0, s29
	s_nop 0
	global_load_lds_dwordx4 v130, s[16:17]
	ds_read_b128 v[154:157], v143 offset:2048
	ds_read_b128 v[158:161], v143 offset:3072
	ds_read_b128 v[162:165], v144
	ds_read_b128 v[166:169], v144 offset:1024
	ds_read_b128 v[170:173], v144 offset:2048
	ds_read_b128 v[174:177], v144 offset:3072
	ds_read_b128 v[186:189], v142 offset:32768
	s_mov_b32 m0, s39
	s_nop 0
	global_load_lds_dwordx4 v132, s[16:17]
	ds_read_b128 v[190:193], v142 offset:33792
	ds_read_b128 v[194:197], v142 offset:34816
	ds_read_b128 v[198:201], v142 offset:35840
	ds_read_b128 v[202:205], v142 offset:36864
	ds_read_b128 v[206:209], v142 offset:37888
	ds_read_b128 v[210:213], v142 offset:38912
	ds_read_b128 v[214:217], v142 offset:39936
	s_waitcnt lgkmcnt(0)
	s_barrier
	s_setprio 1
	s_waitcnt lgkmcnt(0)
	v_mfma_f32_16x16x32_bf16 v[54:57], v[146:149], v[186:189], v[54:57]
	v_mfma_f32_16x16x32_bf16 v[34:37], v[154:157], v[186:189], v[34:37]
	v_mfma_f32_16x16x32_bf16 v[42:45], v[146:149], v[194:197], v[42:45]
	v_mfma_f32_16x16x32_bf16 v[30:33], v[154:157], v[194:197], v[30:33]
	v_mfma_f32_16x16x32_bf16 v[62:65], v[146:149], v[202:205], v[62:65]
	v_mfma_f32_16x16x32_bf16 v[50:53], v[154:157], v[202:205], v[50:53]
	v_mfma_f32_16x16x32_bf16 v[78:81], v[146:149], v[210:213], v[78:81]
	v_mfma_f32_16x16x32_bf16 v[70:73], v[154:157], v[210:213], v[70:73]
	v_mfma_f32_16x16x32_bf16 v[54:57], v[150:153], v[190:193], v[54:57]
	v_mfma_f32_16x16x32_bf16 v[34:37], v[158:161], v[190:193], v[34:37]
	v_mfma_f32_16x16x32_bf16 v[42:45], v[150:153], v[198:201], v[42:45]
	v_mfma_f32_16x16x32_bf16 v[30:33], v[158:161], v[198:201], v[30:33]
	v_mfma_f32_16x16x32_bf16 v[62:65], v[150:153], v[206:209], v[62:65]
	v_mfma_f32_16x16x32_bf16 v[50:53], v[158:161], v[206:209], v[50:53]
	v_mfma_f32_16x16x32_bf16 v[78:81], v[150:153], v[214:217], v[78:81]
	v_mfma_f32_16x16x32_bf16 v[70:73], v[158:161], v[214:217], v[70:73]
	s_setprio 0
	s_setprio 1
	v_mfma_f32_16x16x32_bf16 v[10:13], v[162:165], v[186:189], v[10:13]
	v_mfma_f32_16x16x32_bf16 v[2:5], v[170:173], v[186:189], v[2:5]
	v_mfma_f32_16x16x32_bf16 v[14:17], v[162:165], v[194:197], v[14:17]
	v_mfma_f32_16x16x32_bf16 v[6:9], v[170:173], v[194:197], v[6:9]
	v_mfma_f32_16x16x32_bf16 v[22:25], v[162:165], v[202:205], v[22:25]
	v_mfma_f32_16x16x32_bf16 v[18:21], v[170:173], v[202:205], v[18:21]
	v_mfma_f32_16x16x32_bf16 v[38:41], v[162:165], v[210:213], v[38:41]
	v_mfma_f32_16x16x32_bf16 v[26:29], v[170:173], v[210:213], v[26:29]
	v_mfma_f32_16x16x32_bf16 v[10:13], v[166:169], v[190:193], v[10:13]
	v_mfma_f32_16x16x32_bf16 v[2:5], v[174:177], v[190:193], v[2:5]
	v_mfma_f32_16x16x32_bf16 v[14:17], v[166:169], v[198:201], v[14:17]
	v_mfma_f32_16x16x32_bf16 v[6:9], v[174:177], v[198:201], v[6:9]
	v_mfma_f32_16x16x32_bf16 v[22:25], v[166:169], v[206:209], v[22:25]
	v_mfma_f32_16x16x32_bf16 v[18:21], v[174:177], v[206:209], v[18:21]
	v_mfma_f32_16x16x32_bf16 v[38:41], v[166:169], v[214:217], v[38:41]
	v_mfma_f32_16x16x32_bf16 v[26:29], v[174:177], v[214:217], v[26:29]
	s_setprio 0
	s_waitcnt vmcnt(8)
	s_barrier
	s_mov_b32 m0, s36
	s_add_u32 s48, s10, s4
	s_addc_u32 s49, s11, s5
	s_add_u32 s10, s10, 0x100080
	ds_read_b128 v[186:189], v142 offset:49152
	ds_read_b128 v[190:193], v142 offset:50176
	global_load_lds_dwordx4 v180, s[48:49]
	ds_read_b128 v[194:197], v142 offset:51200
	s_mov_b32 m0, s43
	s_addc_u32 s11, s11, 0
	global_load_lds_dwordx4 v134, s[48:49]
	ds_read_b128 v[198:201], v142 offset:52224
	s_mov_b32 m0, s37
	s_nop 0
	global_load_lds_dwordx4 v180, s[10:11]
	ds_read_b128 v[202:205], v142 offset:53248
	s_mov_b32 m0, s44
	s_nop 0
	global_load_lds_dwordx4 v134, s[10:11]
	ds_read_b128 v[206:209], v142 offset:54272
	s_mov_b32 m0, s40
	s_nop 0
	global_load_lds_dwordx4 v130, s[50:51]
	ds_read_b128 v[210:213], v142 offset:55296
	s_mov_b32 m0, s41
	s_nop 0
	global_load_lds_dwordx4 v132, s[50:51]
	ds_read_b128 v[214:217], v142 offset:56320
	s_waitcnt lgkmcnt(0)
	s_barrier
	s_setprio 1
	s_waitcnt lgkmcnt(0)
	v_mfma_f32_16x16x32_bf16 v[94:97], v[146:149], v[186:189], v[94:97]
	v_mfma_f32_16x16x32_bf16 v[86:89], v[154:157], v[186:189], v[86:89]
	v_mfma_f32_16x16x32_bf16 v[102:105], v[146:149], v[194:197], v[102:105]
	v_mfma_f32_16x16x32_bf16 v[98:101], v[154:157], v[194:197], v[98:101]
	v_mfma_f32_16x16x32_bf16 v[110:113], v[146:149], v[202:205], v[110:113]
	v_mfma_f32_16x16x32_bf16 v[106:109], v[154:157], v[202:205], v[106:109]
	v_mfma_f32_16x16x32_bf16 v[126:129], v[146:149], v[210:213], v[126:129]
	v_mfma_f32_16x16x32_bf16 v[122:125], v[154:157], v[210:213], v[122:125]
	v_mfma_f32_16x16x32_bf16 v[94:97], v[150:153], v[190:193], v[94:97]
	v_mfma_f32_16x16x32_bf16 v[86:89], v[158:161], v[190:193], v[86:89]
	v_mfma_f32_16x16x32_bf16 v[102:105], v[150:153], v[198:201], v[102:105]
	v_mfma_f32_16x16x32_bf16 v[98:101], v[158:161], v[198:201], v[98:101]
	v_mfma_f32_16x16x32_bf16 v[110:113], v[150:153], v[206:209], v[110:113]
	v_mfma_f32_16x16x32_bf16 v[106:109], v[158:161], v[206:209], v[106:109]
	v_mfma_f32_16x16x32_bf16 v[126:129], v[150:153], v[214:217], v[126:129]
	v_mfma_f32_16x16x32_bf16 v[122:125], v[158:161], v[214:217], v[122:125]
	s_setprio 0
	s_setprio 1
	v_mfma_f32_16x16x32_bf16 v[58:61], v[162:165], v[186:189], v[58:61]
	v_mfma_f32_16x16x32_bf16 v[46:49], v[170:173], v[186:189], v[46:49]
	v_mfma_f32_16x16x32_bf16 v[74:77], v[162:165], v[194:197], v[74:77]
	v_mfma_f32_16x16x32_bf16 v[66:69], v[170:173], v[194:197], v[66:69]
	v_mfma_f32_16x16x32_bf16 v[90:93], v[162:165], v[202:205], v[90:93]
	v_mfma_f32_16x16x32_bf16 v[82:85], v[170:173], v[202:205], v[82:85]
	v_mfma_f32_16x16x32_bf16 v[118:121], v[162:165], v[210:213], v[118:121]
	v_mfma_f32_16x16x32_bf16 v[114:117], v[170:173], v[210:213], v[114:117]
	v_mfma_f32_16x16x32_bf16 v[58:61], v[166:169], v[190:193], v[58:61]
	v_mfma_f32_16x16x32_bf16 v[46:49], v[174:177], v[190:193], v[46:49]
	v_mfma_f32_16x16x32_bf16 v[74:77], v[166:169], v[198:201], v[74:77]
	v_mfma_f32_16x16x32_bf16 v[66:69], v[174:177], v[198:201], v[66:69]
	v_mfma_f32_16x16x32_bf16 v[90:93], v[166:169], v[206:209], v[90:93]
	v_mfma_f32_16x16x32_bf16 v[82:85], v[174:177], v[206:209], v[82:85]
	v_mfma_f32_16x16x32_bf16 v[118:121], v[166:169], v[214:217], v[118:121]
	v_mfma_f32_16x16x32_bf16 v[114:117], v[174:177], v[214:217], v[114:117]
	s_setprio 0
	s_waitcnt vmcnt(8)
	s_barrier
	s_add_i32 s18, s18, 2
	s_add_u32 s6, s6, 0x100
	s_addc_u32 s7, s7, 0
	s_cmp_gt_u32 s18, 61
	s_cbranch_scc0 .LBB0_896
	s_branch .Lmy_d896X

; #define PG8_BAR __builtin_amdgcn_s_barrier()
; template <class Epi, class Sched, bool ALIGN_EPI, class Hook = NoHook>
; __device__ __forceinline__ void gemm_phase(LAS unsigned char* lds, const Gemm g, const Sched& S, const Epi& E, const Hook& H = Hook()) {
;     ...
;         if constexpr (ALIGN_EPI) { if (wr == 0) PG8_BAR; }
.Lmy_d896X:
	s_cmpk_lt_u32 s22, 0x100
	s_cbranch_scc0 .LBB0_899
	s_barrier

; #define PG8_STAGE(bufoff, gbase, voff) do { _Pragma("unroll") for (int _i = 0; _i < 2; ++_i) \
;         __builtin_amdgcn_global_load_lds((const unsigned*)((const char*)(gbase) + (voff)[_i]), (LAS unsigned*)(lds + (bufoff) + ldsw + _i * 8192), 16, 0, 0); } while (0)
; #define PG8_LDA(dst, b, h) do { _Pragma("unroll") for (int m = 0; m < 4; ++m) _Pragma("unroll") for (int k = 0; k < 2; ++k) dst[m][k] = *(const LAS bf16x8*)(lds + PG8_SA(b, h) + aoff + m * 2048 + k * 1024); } while (0)
; #define PG8_LDB(dst, b, h) do { _Pragma("unroll") for (int n = 0; n < 2; ++n) _Pragma("unroll") for (int k = 0; k < 2; ++k) dst[n][k] = *(const LAS bf16x8*)(lds + PG8_SB(b, h) + boff + n * 2048 + k * 1024); } while (0)
; #define PG8_SCHED __builtin_amdgcn_sched_barrier(0)
; template <class Epi, class Sched, bool ALIGN_EPI, class Hook = NoHook>
; __device__ __forceinline__ void gemm_phase(LAS unsigned char* lds, const Gemm g, const Sched& S, const Epi& E, const Hook& H = Hook()) {
;     ...
;         for (int t = tb; t < te; t += 2) {
;             const bool last = (t == nt - 2);
;             const char* a1 = cA + (size_t)(t + 1) * kstep;
;             const char* a2 = last ? nA : cA + (size_t)(t + 2) * kstep; const char* b2 = last ? nB : cB + (size_t)(t + 2) * kstep;
;             const char* a3 = a2 + kstep; const char* b3 = b2 + kstep;
;             if (last && has_next) S.a_ready(nxt);
;             PG8_LDB(B0, 0, 0); PG8_LDB(B1, 0, 1); PG8_SCHED; PG8_LDA(At, 0, 0); PG8_STAGE(PG8_SA(1, 1), a1 + hA, voffA);
;     ...
;         for (int a = 0; a < 2; ++a)
; #pragma unroll
;             for (int b = 0; b < 2; ++b)
; #pragma unroll
;                 for (int m = 0; m < 4; ++m)
; #pragma unroll
;                     for (int n = 0; n < 2; ++n) acc[a][b][m][n] = (f32x4){0.f, 0.f, 0.f, 0.f};
;         cur = nxt; cA = nA; cB = nB; ++ui;
.LBB0_1000:
	s_ashr_i32 s35, s34, 31
	s_lshl_b64 s[36:37], s[34:35], 21
	s_add_u32 s36, s8, s36
	s_addc_u32 s37, s9, s37
	s_and_b64 s[38:39], s[4:5], exec
	s_cselect_b32 s35, s37, s7
	s_cselect_b32 s66, s36, s6
	s_ashr_i32 s31, s30, 31
	s_lshl_b64 s[38:39], s[30:31], 21
	v_readlane_b32 s31, v254, 52
	s_add_u32 s38, s31, s38
	v_readlane_b32 s31, v254, 53
	s_addc_u32 s39, s31, s39
	s_and_b64 s[44:45], s[4:5], exec
	s_cselect_b32 s31, s39, s43
	s_cselect_b32 s67, s38, s42
	s_add_u32 s68, s42, 0x100
	v_mov_b32_e32 v178, 0
	s_addc_u32 s69, s43, 0
	s_mov_b32 s70, -2
	v_mov_b32_e32 v179, v178
	v_mov_b32_e32 v180, v178
	v_mov_b32_e32 v181, v178
	v_mov_b32_e32 v98, v178
	v_mov_b32_e32 v99, v178
	v_mov_b32_e32 v100, v178
	v_mov_b32_e32 v101, v178
	v_mov_b32_e32 v174, v178
	v_mov_b32_e32 v175, v178
	v_mov_b32_e32 v176, v178
	v_mov_b32_e32 v177, v178
	v_mov_b32_e32 v94, v178
	v_mov_b32_e32 v95, v178
	v_mov_b32_e32 v96, v178
	v_mov_b32_e32 v97, v178
	v_mov_b32_e32 v10, v178
	v_mov_b32_e32 v11, v178
	v_mov_b32_e32 v12, v178
	v_mov_b32_e32 v13, v178
	v_mov_b32_e32 v14, v178
	v_mov_b32_e32 v15, v178
	v_mov_b32_e32 v16, v178
	v_mov_b32_e32 v17, v178
	v_mov_b32_e32 v2, v178
	v_mov_b32_e32 v3, v178
	v_mov_b32_e32 v4, v178
	v_mov_b32_e32 v5, v178
	v_mov_b32_e32 v6, v178
	v_mov_b32_e32 v7, v178
	v_mov_b32_e32 v8, v178
	v_mov_b32_e32 v9, v178
	v_mov_b32_e32 v26, v178
	v_mov_b32_e32 v27, v178
	v_mov_b32_e32 v28, v178
	v_mov_b32_e32 v29, v178
	v_mov_b32_e32 v30, v178
	v_mov_b32_e32 v31, v178
	v_mov_b32_e32 v32, v178
	v_mov_b32_e32 v33, v178
	v_mov_b32_e32 v18, v178
	v_mov_b32_e32 v19, v178
	v_mov_b32_e32 v20, v178
	v_mov_b32_e32 v21, v178
	v_mov_b32_e32 v34, v178
	v_mov_b32_e32 v35, v178
	v_mov_b32_e32 v36, v178
	v_mov_b32_e32 v37, v178
	v_mov_b32_e32 v50, v178
	v_mov_b32_e32 v51, v178
	v_mov_b32_e32 v52, v178
	v_mov_b32_e32 v53, v178
	v_mov_b32_e32 v58, v178
	v_mov_b32_e32 v59, v178
	v_mov_b32_e32 v60, v178
	v_mov_b32_e32 v61, v178
	v_mov_b32_e32 v38, v178
	v_mov_b32_e32 v39, v178
	v_mov_b32_e32 v40, v178
	v_mov_b32_e32 v41, v178
	v_mov_b32_e32 v42, v178
	v_mov_b32_e32 v43, v178
	v_mov_b32_e32 v44, v178
	v_mov_b32_e32 v45, v178
	v_mov_b32_e32 v22, v178
	v_mov_b32_e32 v23, v178
	v_mov_b32_e32 v24, v178
	v_mov_b32_e32 v25, v178
	v_mov_b32_e32 v46, v178
	v_mov_b32_e32 v47, v178
	v_mov_b32_e32 v48, v178
	v_mov_b32_e32 v49, v178
	v_mov_b32_e32 v54, v178
	v_mov_b32_e32 v55, v178
	v_mov_b32_e32 v56, v178
	v_mov_b32_e32 v57, v178
	v_mov_b32_e32 v62, v178
	v_mov_b32_e32 v63, v178
	v_mov_b32_e32 v64, v178
	v_mov_b32_e32 v65, v178
	v_mov_b32_e32 v66, v178
	v_mov_b32_e32 v67, v178
	v_mov_b32_e32 v68, v178
	v_mov_b32_e32 v69, v178
	v_mov_b32_e32 v74, v178
	v_mov_b32_e32 v75, v178
	v_mov_b32_e32 v76, v178
	v_mov_b32_e32 v77, v178
	v_mov_b32_e32 v82, v178
	v_mov_b32_e32 v83, v178
	v_mov_b32_e32 v84, v178
	v_mov_b32_e32 v85, v178
	v_mov_b32_e32 v90, v178
	v_mov_b32_e32 v91, v178
	v_mov_b32_e32 v92, v178
	v_mov_b32_e32 v93, v178
	v_mov_b32_e32 v166, v178
	v_mov_b32_e32 v167, v178
	v_mov_b32_e32 v168, v178
	v_mov_b32_e32 v169, v178
	v_mov_b32_e32 v186, v178
	v_mov_b32_e32 v187, v178
	v_mov_b32_e32 v188, v178
	v_mov_b32_e32 v189, v178
	v_mov_b32_e32 v70, v178
	v_mov_b32_e32 v71, v178
	v_mov_b32_e32 v72, v178
	v_mov_b32_e32 v73, v178
	v_mov_b32_e32 v78, v178
	v_mov_b32_e32 v79, v178
	v_mov_b32_e32 v80, v178
	v_mov_b32_e32 v81, v178
	v_mov_b32_e32 v86, v178
	v_mov_b32_e32 v87, v178
	v_mov_b32_e32 v88, v178
	v_mov_b32_e32 v89, v178
	v_mov_b32_e32 v102, v178
	v_mov_b32_e32 v103, v178
	v_mov_b32_e32 v104, v178
	v_mov_b32_e32 v105, v178
	v_mov_b32_e32 v182, v178
	v_mov_b32_e32 v183, v178
	v_mov_b32_e32 v184, v178
	v_mov_b32_e32 v185, v178
	v_mov_b32_e32 v190, v178
	v_mov_b32_e32 v191, v178
	v_mov_b32_e32 v192, v178
	v_mov_b32_e32 v193, v178
	s_and_b64 vcc, exec, s[2:3]
	s_cbranch_vccz .Lmy_d1001B
.LBB0_1001:
	ds_read_b128 v[106:109], v246
	ds_read_b128 v[110:113], v246 offset:1024
	s_add_u32 s42, s6, 0x100
	s_addc_u32 s43, s7, 0
	s_cmp_eq_u32 s70, 60
	s_cselect_b32 s47, s35, s43
	s_cselect_b32 s46, s66, s42
	s_cselect_b32 s45, s31, s69
	s_cselect_b32 s44, s67, s68
	s_add_i32 m0, s51, 0xc000
	s_nop 0
	global_load_lds_dwordx4 v236, s[6:7]
	ds_read_b128 v[114:117], v246 offset:2048
	ds_read_b128 v[118:121], v246 offset:3072
	ds_read_b128 v[122:125], v247
	ds_read_b128 v[126:129], v247 offset:1024
	ds_read_b128 v[130:133], v247 offset:2048
	ds_read_b128 v[134:137], v247 offset:3072
	ds_read_b128 v[138:141], v248
	s_add_i32 m0, s51, 0xe000
	s_nop 0
	global_load_lds_dwordx4 v238, s[6:7]
	ds_read_b128 v[142:145], v248 offset:1024
	ds_read_b128 v[146:149], v248 offset:2048
	ds_read_b128 v[150:153], v248 offset:3072
	ds_read_b128 v[154:157], v248 offset:4096
	ds_read_b128 v[158:161], v248 offset:5120
	ds_read_b128 v[162:165], v248 offset:6144
	ds_read_b128 v[170:173], v248 offset:7168
	s_waitcnt lgkmcnt(0)
	s_barrier
; #define PG8_STAGE(bufoff, gbase, voff) do { _Pragma("unroll") for (int _i = 0; _i < 2; ++_i) \
;         __builtin_amdgcn_global_load_lds((const unsigned*)((const char*)(gbase) + (voff)[_i]), (LAS unsigned*)(lds + (bufoff) + ldsw + _i * 8192), 16, 0, 0); } while (0)
; #define PG8_LDA(dst, b, h) do { _Pragma("unroll") for (int m = 0; m < 4; ++m) _Pragma("unroll") for (int k = 0; k < 2; ++k) dst[m][k] = *(const LAS bf16x8*)(lds + PG8_SA(b, h) + aoff + m * 2048 + k * 1024); } while (0)
; #define PG8_LDB(dst, b, h) do { _Pragma("unroll") for (int n = 0; n < 2; ++n) _Pragma("unroll") for (int k = 0; k < 2; ++k) dst[n][k] = *(const LAS bf16x8*)(lds + PG8_SB(b, h) + boff + n * 2048 + k * 1024); } while (0)
; #define PG8_MMA(ai, bj, At, Bt) do { __builtin_amdgcn_s_setprio(1); _Pragma("unroll") for (int m = 0; m < 4; ++m) _Pragma("unroll") for (int n = 0; n < 2; ++n) _Pragma("unroll") for (int k = 0; k < 2; ++k) \
;         acc[ai][bj][m][n] = __builtin_amdgcn_mfma_f32_16x16x32_bf16(Bt[n][k], At[m][k], acc[ai][bj][m][n], 0, 0, 0); __builtin_amdgcn_s_setprio(0); } while (0)
; #define PG8_WAIT_V(n) asm volatile("s_waitcnt vmcnt(" #n ")" ::: "memory")
; #define PG8_WAIT_L(n) asm volatile("s_waitcnt lgkmcnt(" #n ")" ::: "memory")
; #define PG8_BAR __builtin_amdgcn_s_barrier()
; #define PG8_SCHED __builtin_amdgcn_sched_barrier(0)
; template <class Epi, class Sched, bool ALIGN_EPI, class Hook = NoHook>
; __device__ __forceinline__ void gemm_phase(LAS unsigned char* lds, const Gemm g, const Sched& S, const Epi& E, const Hook& H = Hook()) {
;     ...
;             PG8_LDB(B0, 0, 0); PG8_LDB(B1, 0, 1); PG8_SCHED; PG8_LDA(At, 0, 0); PG8_STAGE(PG8_SA(1, 1), a1 + hA, voffA);
;             PG8_WAIT_V(8); PG8_WAIT_L(0); PG8_BAR; PG8_MMA(0, 0, At, B0); PG8_MMA(0, 1, At, B1); PG8_BAR; PG8_SCHED;
;             PG8_LDA(At, 0, 1); PG8_STAGE(PG8_SB(0, 0), b2, voffB); PG8_STAGE(PG8_SB(0, 1), b2 + hB, voffB); PG8_STAGE(PG8_SA(0, 0), a2, voffA);
;             PG8_WAIT_V(8); PG8_WAIT_L(0); PG8_BAR; PG8_MMA(1, 0, At, B0); PG8_MMA(1, 1, At, B1); PG8_BAR; PG8_SCHED;
	s_setprio 1
	s_waitcnt lgkmcnt(0)
	v_mfma_f32_16x16x32_bf16 v[190:193], v[106:109], v[138:141], v[190:193]
	v_mfma_f32_16x16x32_bf16 v[178:181], v[114:117], v[138:141], v[178:181]
	v_mfma_f32_16x16x32_bf16 v[182:185], v[106:109], v[146:149], v[182:185]
	v_mfma_f32_16x16x32_bf16 v[98:101], v[114:117], v[146:149], v[98:101]
	v_mfma_f32_16x16x32_bf16 v[102:105], v[106:109], v[154:157], v[102:105]
	v_mfma_f32_16x16x32_bf16 v[86:89], v[114:117], v[154:157], v[86:89]
	v_mfma_f32_16x16x32_bf16 v[78:81], v[106:109], v[162:165], v[78:81]
	v_mfma_f32_16x16x32_bf16 v[70:73], v[114:117], v[162:165], v[70:73]
	v_mfma_f32_16x16x32_bf16 v[190:193], v[110:113], v[142:145], v[190:193]
	v_mfma_f32_16x16x32_bf16 v[178:181], v[118:121], v[142:145], v[178:181]
	v_mfma_f32_16x16x32_bf16 v[182:185], v[110:113], v[150:153], v[182:185]
	v_mfma_f32_16x16x32_bf16 v[98:101], v[118:121], v[150:153], v[98:101]
	v_mfma_f32_16x16x32_bf16 v[102:105], v[110:113], v[158:161], v[102:105]
	v_mfma_f32_16x16x32_bf16 v[86:89], v[118:121], v[158:161], v[86:89]
	v_mfma_f32_16x16x32_bf16 v[78:81], v[110:113], v[170:173], v[78:81]
	v_mfma_f32_16x16x32_bf16 v[70:73], v[118:121], v[170:173], v[70:73]
	s_setprio 0
	s_setprio 1
	v_mfma_f32_16x16x32_bf16 v[186:189], v[122:125], v[138:141], v[186:189]
	v_mfma_f32_16x16x32_bf16 v[138:141], v[130:133], v[138:141], v[174:177]
	v_mfma_f32_16x16x32_bf16 v[94:97], v[130:133], v[146:149], v[94:97]
	v_mfma_f32_16x16x32_bf16 v[90:93], v[122:125], v[154:157], v[90:93]
	v_mfma_f32_16x16x32_bf16 v[82:85], v[130:133], v[154:157], v[82:85]
	v_mfma_f32_16x16x32_bf16 v[74:77], v[122:125], v[162:165], v[74:77]
	v_mfma_f32_16x16x32_bf16 v[66:69], v[130:133], v[162:165], v[66:69]
	v_mfma_f32_16x16x32_bf16 v[186:189], v[126:129], v[142:145], v[186:189]
	v_mfma_f32_16x16x32_bf16 v[138:141], v[134:137], v[142:145], v[138:141]
	v_mfma_f32_16x16x32_bf16 v[142:145], v[122:125], v[146:149], v[166:169]
	v_mfma_f32_16x16x32_bf16 v[94:97], v[134:137], v[150:153], v[94:97]
	v_mfma_f32_16x16x32_bf16 v[90:93], v[126:129], v[158:161], v[90:93]
	v_mfma_f32_16x16x32_bf16 v[82:85], v[134:137], v[158:161], v[82:85]
	v_mfma_f32_16x16x32_bf16 v[74:77], v[126:129], v[170:173], v[74:77]
	v_mfma_f32_16x16x32_bf16 v[66:69], v[134:137], v[170:173], v[66:69]
	v_mfma_f32_16x16x32_bf16 v[142:145], v[126:129], v[150:153], v[142:145]
	s_setprio 0
	s_waitcnt vmcnt(8)
	s_barrier
	s_add_i32 s6, s63, s29
	s_mov_b32 m0, s6
	ds_read_b128 v[146:149], v248 offset:16384
	ds_read_b128 v[150:153], v248 offset:17408
	global_load_lds_dwordx4 v232, s[44:45]
	ds_read_b128 v[154:157], v248 offset:18432
	s_add_i32 m0, s6, 0x2000
	s_add_u32 s6, s44, 0x100000
	s_addc_u32 s7, s45, 0
	s_add_i32 s71, s64, s29
	global_load_lds_dwordx4 v228, s[44:45]
	ds_read_b128 v[158:161], v248 offset:19456
	s_mov_b32 m0, s71
	s_nop 0
	global_load_lds_dwordx4 v232, s[6:7]
	ds_read_b128 v[162:165], v248 offset:20480
	s_add_i32 m0, s71, 0x2000
	s_nop 0
	global_load_lds_dwordx4 v228, s[6:7]
	ds_read_b128 v[166:169], v248 offset:21504
	s_mov_b32 m0, s51
	s_nop 0
	global_load_lds_dwordx4 v234, s[46:47]
	ds_read_b128 v[170:173], v248 offset:22528
	s_mov_b32 m0, s52
	s_nop 0
	global_load_lds_dwordx4 v230, s[46:47]
	ds_read_b128 v[174:177], v248 offset:23552
	s_waitcnt lgkmcnt(0)
	s_barrier
	s_setprio 1
	s_waitcnt lgkmcnt(0)
	v_mfma_f32_16x16x32_bf16 v[62:65], v[106:109], v[146:149], v[62:65]
	v_mfma_f32_16x16x32_bf16 v[54:57], v[114:117], v[146:149], v[54:57]
	v_mfma_f32_16x16x32_bf16 v[46:49], v[106:109], v[154:157], v[46:49]
	v_mfma_f32_16x16x32_bf16 v[22:25], v[114:117], v[154:157], v[22:25]
	v_mfma_f32_16x16x32_bf16 v[42:45], v[106:109], v[162:165], v[42:45]
	v_mfma_f32_16x16x32_bf16 v[10:13], v[114:117], v[162:165], v[10:13]
	v_mfma_f32_16x16x32_bf16 v[38:41], v[106:109], v[170:173], v[38:41]
	v_mfma_f32_16x16x32_bf16 v[14:17], v[114:117], v[170:173], v[14:17]
	v_mfma_f32_16x16x32_bf16 v[62:65], v[110:113], v[150:153], v[62:65]
	v_mfma_f32_16x16x32_bf16 v[54:57], v[118:121], v[150:153], v[54:57]
	v_mfma_f32_16x16x32_bf16 v[46:49], v[110:113], v[158:161], v[46:49]
	v_mfma_f32_16x16x32_bf16 v[22:25], v[118:121], v[158:161], v[22:25]
	v_mfma_f32_16x16x32_bf16 v[42:45], v[110:113], v[166:169], v[42:45]
	v_mfma_f32_16x16x32_bf16 v[10:13], v[118:121], v[166:169], v[10:13]
	v_mfma_f32_16x16x32_bf16 v[38:41], v[110:113], v[174:177], v[38:41]
	v_mfma_f32_16x16x32_bf16 v[14:17], v[118:121], v[174:177], v[14:17]
	s_setprio 0
	s_setprio 1
	v_mfma_f32_16x16x32_bf16 v[58:61], v[122:125], v[146:149], v[58:61]
	v_mfma_f32_16x16x32_bf16 v[50:53], v[130:133], v[146:149], v[50:53]
	v_mfma_f32_16x16x32_bf16 v[34:37], v[122:125], v[154:157], v[34:37]
	v_mfma_f32_16x16x32_bf16 v[18:21], v[130:133], v[154:157], v[18:21]
	v_mfma_f32_16x16x32_bf16 v[30:33], v[122:125], v[162:165], v[30:33]
	v_mfma_f32_16x16x32_bf16 v[2:5], v[130:133], v[162:165], v[2:5]
	v_mfma_f32_16x16x32_bf16 v[26:29], v[122:125], v[170:173], v[26:29]
	v_mfma_f32_16x16x32_bf16 v[6:9], v[130:133], v[170:173], v[6:9]
	v_mfma_f32_16x16x32_bf16 v[58:61], v[126:129], v[150:153], v[58:61]
	v_mfma_f32_16x16x32_bf16 v[50:53], v[134:137], v[150:153], v[50:53]
	v_mfma_f32_16x16x32_bf16 v[34:37], v[126:129], v[158:161], v[34:37]
	v_mfma_f32_16x16x32_bf16 v[18:21], v[134:137], v[158:161], v[18:21]
	v_mfma_f32_16x16x32_bf16 v[30:33], v[126:129], v[166:169], v[30:33]
	v_mfma_f32_16x16x32_bf16 v[2:5], v[134:137], v[166:169], v[2:5]
	v_mfma_f32_16x16x32_bf16 v[26:29], v[126:129], v[174:177], v[26:29]
	v_mfma_f32_16x16x32_bf16 v[6:9], v[134:137], v[174:177], v[6:9]
	s_setprio 0
	s_waitcnt vmcnt(8)
	s_barrier
; #define PG8_STAGE(bufoff, gbase, voff) do { _Pragma("unroll") for (int _i = 0; _i < 2; ++_i) \
;         __builtin_amdgcn_global_load_lds((const unsigned*)((const char*)(gbase) + (voff)[_i]), (LAS unsigned*)(lds + (bufoff) + ldsw + _i * 8192), 16, 0, 0); } while (0)
; #define PG8_LDA(dst, b, h) do { _Pragma("unroll") for (int m = 0; m < 4; ++m) _Pragma("unroll") for (int k = 0; k < 2; ++k) dst[m][k] = *(const LAS bf16x8*)(lds + PG8_SA(b, h) + aoff + m * 2048 + k * 1024); } while (0)
; #define PG8_LDB(dst, b, h) do { _Pragma("unroll") for (int n = 0; n < 2; ++n) _Pragma("unroll") for (int k = 0; k < 2; ++k) dst[n][k] = *(const LAS bf16x8*)(lds + PG8_SB(b, h) + boff + n * 2048 + k * 1024); } while (0)
; #define PG8_MMA(ai, bj, At, Bt) do { __builtin_amdgcn_s_setprio(1); _Pragma("unroll") for (int m = 0; m < 4; ++m) _Pragma("unroll") for (int n = 0; n < 2; ++n) _Pragma("unroll") for (int k = 0; k < 2; ++k) \
;         acc[ai][bj][m][n] = __builtin_amdgcn_mfma_f32_16x16x32_bf16(Bt[n][k], At[m][k], acc[ai][bj][m][n], 0, 0, 0); __builtin_amdgcn_s_setprio(0); } while (0)
; #define PG8_WAIT_V(n) asm volatile("s_waitcnt vmcnt(" #n ")" ::: "memory")
; #define PG8_WAIT_L(n) asm volatile("s_waitcnt lgkmcnt(" #n ")" ::: "memory")
; #define PG8_BAR __builtin_amdgcn_s_barrier()
; #define PG8_SCHED __builtin_amdgcn_sched_barrier(0)
; template <class Epi, class Sched, bool ALIGN_EPI, class Hook = NoHook>
; __device__ __forceinline__ void gemm_phase(LAS unsigned char* lds, const Gemm g, const Sched& S, const Epi& E, const Hook& H = Hook()) {
;     ...
;             PG8_LDB(B0, 1, 0); PG8_LDB(B1, 1, 1); PG8_SCHED; PG8_LDA(At, 1, 0); PG8_STAGE(PG8_SA(0, 1), a2 + hA, voffA);
;             PG8_WAIT_V(8); PG8_WAIT_L(0); PG8_BAR; PG8_MMA(0, 0, At, B0); PG8_MMA(0, 1, At, B1); PG8_BAR; PG8_SCHED;
;             PG8_LDA(At, 1, 1); PG8_STAGE(PG8_SB(1, 0), b3, voffB); PG8_STAGE(PG8_SB(1, 1), b3 + hB, voffB); PG8_STAGE(PG8_SA(1, 0), a3, voffA);
;             PG8_WAIT_V(8); PG8_WAIT_L(0); PG8_BAR; PG8_MMA(1, 0, At, B0); PG8_MMA(1, 1, At, B1); PG8_BAR; PG8_SCHED;
;         }
	s_add_i32 s71, 0, 0x18000
	s_add_i32 s72, 0, 0x1c000
	v_add_u32_e32 v118, s71, v245
	v_add_u32_e32 v134, s72, v245
	ds_read_b128 v[106:109], v118
	ds_read_b128 v[110:113], v118 offset:1024
	s_add_u32 s6, s46, 0x8000
	s_addc_u32 s7, s47, 0
	s_mov_b32 m0, s53
	s_nop 0
	global_load_lds_dwordx4 v234, s[6:7]
	ds_read_b128 v[114:117], v118 offset:2048
	ds_read_b128 v[118:121], v118 offset:3072
	ds_read_b128 v[122:125], v134
	ds_read_b128 v[126:129], v134 offset:1024
	ds_read_b128 v[130:133], v134 offset:2048
	ds_read_b128 v[134:137], v134 offset:3072
	ds_read_b128 v[146:149], v248 offset:32768
	s_mov_b32 m0, s54
	s_nop 0
	global_load_lds_dwordx4 v230, s[6:7]
	ds_read_b128 v[150:153], v248 offset:33792
	ds_read_b128 v[154:157], v248 offset:34816
	ds_read_b128 v[158:161], v248 offset:35840
	ds_read_b128 v[162:165], v248 offset:36864
	ds_read_b128 v[170:173], v248 offset:37888
	ds_read_b128 v[194:197], v248 offset:38912
	ds_read_b128 v[198:201], v248 offset:39936
	s_waitcnt lgkmcnt(0)
	s_barrier
	s_setprio 1
	s_waitcnt lgkmcnt(0)
	v_mfma_f32_16x16x32_bf16 v[166:169], v[106:109], v[146:149], v[190:193]
	v_mfma_f32_16x16x32_bf16 v[190:193], v[110:113], v[150:153], v[166:169]
	v_mfma_f32_16x16x32_bf16 v[166:169], v[114:117], v[146:149], v[178:181]
	v_mfma_f32_16x16x32_bf16 v[178:181], v[118:121], v[150:153], v[166:169]
	v_mfma_f32_16x16x32_bf16 v[166:169], v[106:109], v[154:157], v[182:185]
	v_mfma_f32_16x16x32_bf16 v[98:101], v[114:117], v[154:157], v[98:101]
	v_mfma_f32_16x16x32_bf16 v[102:105], v[106:109], v[162:165], v[102:105]
	v_mfma_f32_16x16x32_bf16 v[86:89], v[114:117], v[162:165], v[86:89]
	v_mfma_f32_16x16x32_bf16 v[78:81], v[106:109], v[194:197], v[78:81]
	v_mfma_f32_16x16x32_bf16 v[70:73], v[114:117], v[194:197], v[70:73]
	v_mfma_f32_16x16x32_bf16 v[182:185], v[110:113], v[158:161], v[166:169]
	v_mfma_f32_16x16x32_bf16 v[98:101], v[118:121], v[158:161], v[98:101]
	v_mfma_f32_16x16x32_bf16 v[102:105], v[110:113], v[170:173], v[102:105]
	v_mfma_f32_16x16x32_bf16 v[86:89], v[118:121], v[170:173], v[86:89]
	v_mfma_f32_16x16x32_bf16 v[78:81], v[110:113], v[198:201], v[78:81]
	v_mfma_f32_16x16x32_bf16 v[70:73], v[118:121], v[198:201], v[70:73]
	s_setprio 0
	s_setprio 1
	v_mfma_f32_16x16x32_bf16 v[138:141], v[130:133], v[146:149], v[138:141]
	v_mfma_f32_16x16x32_bf16 v[166:169], v[122:125], v[146:149], v[186:189]
	v_mfma_f32_16x16x32_bf16 v[174:177], v[134:137], v[150:153], v[138:141]
	v_mfma_f32_16x16x32_bf16 v[138:141], v[122:125], v[154:157], v[142:145]
	v_mfma_f32_16x16x32_bf16 v[94:97], v[130:133], v[154:157], v[94:97]
	v_mfma_f32_16x16x32_bf16 v[90:93], v[122:125], v[162:165], v[90:93]
	v_mfma_f32_16x16x32_bf16 v[82:85], v[130:133], v[162:165], v[82:85]
	v_mfma_f32_16x16x32_bf16 v[74:77], v[122:125], v[194:197], v[74:77]
	v_mfma_f32_16x16x32_bf16 v[66:69], v[130:133], v[194:197], v[66:69]
	v_mfma_f32_16x16x32_bf16 v[186:189], v[126:129], v[150:153], v[166:169]
	v_mfma_f32_16x16x32_bf16 v[166:169], v[126:129], v[158:161], v[138:141]
	v_mfma_f32_16x16x32_bf16 v[94:97], v[134:137], v[158:161], v[94:97]
	v_mfma_f32_16x16x32_bf16 v[90:93], v[126:129], v[170:173], v[90:93]
	v_mfma_f32_16x16x32_bf16 v[82:85], v[134:137], v[170:173], v[82:85]
	v_mfma_f32_16x16x32_bf16 v[74:77], v[126:129], v[198:201], v[74:77]
	v_mfma_f32_16x16x32_bf16 v[66:69], v[134:137], v[198:201], v[66:69]
	s_setprio 0
	s_waitcnt vmcnt(8)
	s_barrier
	s_add_i32 s6, s71, s29
	s_add_u32 s74, s44, s14
	s_addc_u32 s75, s45, s15
	s_mov_b32 m0, s6
	ds_read_b128 v[138:141], v248 offset:49152
	ds_read_b128 v[142:145], v248 offset:50176
	global_load_lds_dwordx4 v232, s[74:75]
	ds_read_b128 v[146:149], v248 offset:51200
	s_add_i32 m0, s6, 0x2000
	s_add_u32 s6, s44, 0x100080
	s_addc_u32 s7, s45, 0
	s_add_i32 s44, s72, s29
	global_load_lds_dwordx4 v228, s[74:75]
	ds_read_b128 v[150:153], v248 offset:52224
	s_mov_b32 m0, s44
	s_nop 0
	global_load_lds_dwordx4 v232, s[6:7]
	ds_read_b128 v[154:157], v248 offset:53248
	s_add_i32 m0, s44, 0x2000
	s_nop 0
	global_load_lds_dwordx4 v228, s[6:7]
	ds_read_b128 v[158:161], v248 offset:54272
	s_add_u32 s78, s46, s14
	s_addc_u32 s79, s47, s15
	s_mov_b32 m0, s57
	s_nop 0
	global_load_lds_dwordx4 v234, s[78:79]
	ds_read_b128 v[162:165], v248 offset:55296
	s_mov_b32 m0, s58
	s_nop 0
	global_load_lds_dwordx4 v230, s[78:79]
	ds_read_b128 v[170:173], v248 offset:56320
	s_waitcnt lgkmcnt(0)
	s_barrier
	s_setprio 1
	s_waitcnt lgkmcnt(0)
	v_mfma_f32_16x16x32_bf16 v[62:65], v[106:109], v[138:141], v[62:65]
	v_mfma_f32_16x16x32_bf16 v[54:57], v[114:117], v[138:141], v[54:57]
	v_mfma_f32_16x16x32_bf16 v[46:49], v[106:109], v[146:149], v[46:49]
	v_mfma_f32_16x16x32_bf16 v[22:25], v[114:117], v[146:149], v[22:25]
	v_mfma_f32_16x16x32_bf16 v[42:45], v[106:109], v[154:157], v[42:45]
	v_mfma_f32_16x16x32_bf16 v[10:13], v[114:117], v[154:157], v[10:13]
	v_mfma_f32_16x16x32_bf16 v[38:41], v[106:109], v[162:165], v[38:41]
	v_mfma_f32_16x16x32_bf16 v[14:17], v[114:117], v[162:165], v[14:17]
	v_mfma_f32_16x16x32_bf16 v[62:65], v[110:113], v[142:145], v[62:65]
	v_mfma_f32_16x16x32_bf16 v[54:57], v[118:121], v[142:145], v[54:57]
	v_mfma_f32_16x16x32_bf16 v[46:49], v[110:113], v[150:153], v[46:49]
	v_mfma_f32_16x16x32_bf16 v[22:25], v[118:121], v[150:153], v[22:25]
	v_mfma_f32_16x16x32_bf16 v[42:45], v[110:113], v[158:161], v[42:45]
	v_mfma_f32_16x16x32_bf16 v[10:13], v[118:121], v[158:161], v[10:13]
	v_mfma_f32_16x16x32_bf16 v[38:41], v[110:113], v[170:173], v[38:41]
	v_mfma_f32_16x16x32_bf16 v[14:17], v[118:121], v[170:173], v[14:17]
	s_setprio 0
	s_setprio 1
	v_mfma_f32_16x16x32_bf16 v[58:61], v[122:125], v[138:141], v[58:61]
	v_mfma_f32_16x16x32_bf16 v[50:53], v[130:133], v[138:141], v[50:53]
	v_mfma_f32_16x16x32_bf16 v[34:37], v[122:125], v[146:149], v[34:37]
	v_mfma_f32_16x16x32_bf16 v[18:21], v[130:133], v[146:149], v[18:21]
	v_mfma_f32_16x16x32_bf16 v[30:33], v[122:125], v[154:157], v[30:33]
	v_mfma_f32_16x16x32_bf16 v[2:5], v[130:133], v[154:157], v[2:5]
	v_mfma_f32_16x16x32_bf16 v[26:29], v[122:125], v[162:165], v[26:29]
	v_mfma_f32_16x16x32_bf16 v[6:9], v[130:133], v[162:165], v[6:9]
	v_mfma_f32_16x16x32_bf16 v[58:61], v[126:129], v[142:145], v[58:61]
	v_mfma_f32_16x16x32_bf16 v[50:53], v[134:137], v[142:145], v[50:53]
	v_mfma_f32_16x16x32_bf16 v[34:37], v[126:129], v[150:153], v[34:37]
	v_mfma_f32_16x16x32_bf16 v[18:21], v[134:137], v[150:153], v[18:21]
	v_mfma_f32_16x16x32_bf16 v[30:33], v[126:129], v[158:161], v[30:33]
	v_mfma_f32_16x16x32_bf16 v[2:5], v[134:137], v[158:161], v[2:5]
	v_mfma_f32_16x16x32_bf16 v[26:29], v[126:129], v[170:173], v[26:29]
	v_mfma_f32_16x16x32_bf16 v[6:9], v[134:137], v[170:173], v[6:9]
	s_setprio 0
	s_waitcnt vmcnt(8)
	s_barrier
	s_add_i32 s70, s70, 2
	s_add_u32 s68, s68, 0x100
	s_addc_u32 s69, s69, 0
	s_cmp_gt_u32 s70, 61
	s_mov_b64 s[6:7], s[42:43]
	s_cbranch_scc0 .LBB0_1001
	s_branch .Lmy_d1001X

; #define PG8_BAR __builtin_amdgcn_s_barrier()
; template <class Epi, class Sched, bool ALIGN_EPI, class Hook = NoHook>
; __device__ __forceinline__ void gemm_phase(LAS unsigned char* lds, const Gemm g, const Sched& S, const Epi& E, const Hook& H = Hook()) {
;     ...
;         if constexpr (ALIGN_EPI) { if (wr == 0) PG8_BAR; }
.Lmy_d1001X:
	s_and_b64 vcc, exec, s[2:3]
	s_cbranch_vccz .LBB0_1004
	s_barrier

; #define PG8_STAGE(bufoff, gbase, voff) do { _Pragma("unroll") for (int _i = 0; _i < 2; ++_i) \
;         __builtin_amdgcn_global_load_lds((const unsigned*)((const char*)(gbase) + (voff)[_i]), (LAS unsigned*)(lds + (bufoff) + ldsw + _i * 8192), 16, 0, 0); } while (0)
; #define PG8_WAIT_V(n) asm volatile("s_waitcnt vmcnt(" #n ")" ::: "memory")
; #define PG8_BAR __builtin_amdgcn_s_barrier()
; template <class Epi, class Sched, bool ALIGN_EPI, class Hook = NoHook>
; __device__ __forceinline__ void gemm_phase(LAS unsigned char* lds, const Gemm g, const Sched& S, const Epi& E, const Hook& H = Hook()) {
;     ...
;     f32x4 acc[2][2][4][2];
; #pragma unroll
;     for (int a = 0; a < 2; ++a)
; #pragma unroll
;         for (int b = 0; b < 2; ++b)
; #pragma unroll
;             for (int m = 0; m < 4; ++m)
; #pragma unroll
;                 for (int n = 0; n < 2; ++n) acc[a][b][m][n] = (f32x4){0.f, 0.f, 0.f, 0.f};
;     bf16x8 At[4][2], B0[2][2], B1[2][2];
;     const char* cA = (const char*)g.A + (size_t)cur.pm * tA + (size_t)cur.ka * 2; const char* cB = (const char*)g.Bt + (size_t)cur.pn * 2 * hB + (size_t)cur.ka * 2;
;     S.a_ready(cur);
;     if constexpr (Hook::ON) H.unit_start(cur);
;     PG8_STAGE(PG8_SB(0, 0), cB, voffB); PG8_STAGE(PG8_SB(0, 1), cB + hB, voffB); PG8_STAGE(PG8_SA(0, 0), cA, voffA); PG8_STAGE(PG8_SA(0, 1), cA + hA, voffA);
;     if (wr == 1) PG8_BAR;
;     PG8_WAIT_V(2); PG8_BAR;
;     PG8_STAGE(PG8_SB(1, 0), cB + kstep, voffB); PG8_STAGE(PG8_SA(1, 0), cA + kstep, voffA); PG8_STAGE(PG8_SB(1, 1), cB + hB + kstep, voffB);
;     PG8_WAIT_V(6); PG8_BAR;
.LBB0_1359:
	v_and_b32_e32 v163, 15, v162
	v_and_b32_e32 v17, 48, v162
	v_lshlrev_b32_e32 v18, 2, v162
	s_and_b32 s24, s22, 3
	s_lshl_b32 s2, s23, 13
	v_lshl_or_b32 v17, v163, 6, v17
	v_and_b32_e32 v18, 32, v18
	v_bitop3_b32 v19, v17, s2, v18 bitop3:0xde
	s_lshl_b32 s2, s24, 12
	v_bitop3_b32 v17, v17, s2, v18 bitop3:0xde
	s_mov_b64 s[2:3], 0x80
	s_add_i32 m0, s25, 0x18000
	v_lshl_add_u64 v[8:9], v[8:9], 0, s[2:3]
	s_lshl_b32 s29, s23, 6
	s_waitcnt vmcnt(2)
	s_barrier
	global_load_lds_dwordx4 v[8:9], off
	v_lshl_add_u64 v[6:7], v[6:7], 0, s[2:3]
	s_add_i32 m0, s25, 0x1a000
	s_add_i32 s39, s25, 0x8000
	s_add_i32 s40, s25, 0xa000
	global_load_lds_dwordx4 v[6:7], off
	v_lshl_add_u64 v[4:5], v[4:5], 0, s[2:3]
	s_mov_b32 m0, s39
	s_add_u32 s18, s12, 0x2b0080
	global_load_lds_dwordx4 v[4:5], off
	v_lshl_add_u64 v[2:3], v[2:3], 0, s[2:3]
	s_mov_b32 m0, s40
	s_addc_u32 s19, s13, 0
	global_load_lds_dwordx4 v[2:3], off
	s_add_i32 m0, s25, 0x1c000
	v_lshl_add_u64 v[2:3], s[18:19], 0, v[132:133]
	global_load_lds_dwordx4 v[2:3], off
	v_lshl_add_u64 v[2:3], s[18:19], 0, v[136:137]
	s_add_i32 m0, s25, 0x1e000
	v_lshrrev_b32_e32 v1, 1, v1
	global_load_lds_dwordx4 v[2:3], off
	v_mul_lo_u32 v2, v11, s4
	s_mov_b32 s5, 0x2b000
	v_mad_u64_u32 v[2:3], s[20:21], v1, s5, v[2:3]
	s_bfe_u32 s15, s88, 0x20001
	s_mul_i32 s15, s15, 0x1580000
	s_mul_i32 s20, s33, 0x560000
	s_add_i32 s15, s15, s20
	v_or_b32_e32 v1, v2, v10
	s_add_u32 s20, s96, s15
	v_add_lshl_u32 v2, v1, v12, 1
	v_mov_b32_e32 v3, v133
	s_addc_u32 s21, s97, 0
	v_lshl_add_u64 v[138:139], s[20:21], 0, v[2:3]
	v_lshrrev_b32_e32 v1, 1, v13
	v_mul_lo_u32 v2, v14, s4
	v_mad_u64_u32 v[2:3], s[4:5], v1, s5, v[2:3]
	s_waitcnt vmcnt(6)
	v_or_b32_e32 v1, v2, v15
	s_add_i32 s34, 0, 0x10000
	s_add_i32 s35, 0, 0x14000
	s_add_i32 s36, 0, 0x18000
	s_add_i32 s37, 0, 0x1c000
	v_add_lshl_u32 v2, v1, v16, 1
	v_mov_b32_e32 v3, v133
	s_add_i32 s44, s34, s14
	s_add_i32 s46, s35, s14
	s_add_i32 s48, s36, s14
	s_add_i32 s50, s37, s14
	v_or_b32_e32 v169, s29, v163
	v_lshl_add_u64 v[140:141], s[20:21], 0, v[2:3]
	s_mov_b32 s41, -2
	s_mov_b64 s[4:5], 0x44fb0080
	v_add_u32_e32 v1, s34, v17
	v_add_u32_e32 v142, s35, v17
	v_add_u32_e32 v143, 0, v19
	s_add_i32 s42, s25, 0xc000
	s_add_i32 s43, s25, 0xe000
	s_add_i32 s45, s44, 0x2000
	s_add_i32 s47, s46, 0x2000
	v_add_u32_e32 v144, s36, v17
	v_add_u32_e32 v145, s37, v17
	s_add_i32 s49, s48, 0x2000
	s_add_i32 s51, s50, 0x2000
	v_mov_b32_e32 v114, v133
	v_mov_b32_e32 v115, v133
	v_mov_b32_e32 v116, v133
	v_mov_b32_e32 v117, v133
	v_mov_b32_e32 v118, v133
	v_mov_b32_e32 v119, v133
	v_mov_b32_e32 v120, v133
	v_mov_b32_e32 v121, v133
	v_mov_b32_e32 v62, v133
	v_mov_b32_e32 v63, v133
	v_mov_b32_e32 v64, v133
	v_mov_b32_e32 v65, v133
	v_mov_b32_e32 v78, v133
	v_mov_b32_e32 v79, v133
	v_mov_b32_e32 v80, v133
	v_mov_b32_e32 v81, v133
	v_mov_b32_e32 v46, v133
	v_mov_b32_e32 v47, v133
	v_mov_b32_e32 v48, v133
	v_mov_b32_e32 v49, v133
	v_mov_b32_e32 v66, v133
	v_mov_b32_e32 v67, v133
	v_mov_b32_e32 v68, v133
	v_mov_b32_e32 v69, v133
	v_mov_b32_e32 v34, v133
	v_mov_b32_e32 v35, v133
	v_mov_b32_e32 v36, v133
	v_mov_b32_e32 v37, v133
	v_mov_b32_e32 v38, v133
	v_mov_b32_e32 v39, v133
	v_mov_b32_e32 v40, v133
	v_mov_b32_e32 v41, v133
	v_mov_b32_e32 v122, v133
	v_mov_b32_e32 v123, v133
	v_mov_b32_e32 v124, v133
	v_mov_b32_e32 v125, v133
	v_mov_b32_e32 v126, v133
	v_mov_b32_e32 v127, v133
	v_mov_b32_e32 v128, v133
	v_mov_b32_e32 v129, v133
	v_mov_b32_e32 v102, v133
	v_mov_b32_e32 v103, v133
	v_mov_b32_e32 v104, v133
	v_mov_b32_e32 v105, v133
	v_mov_b32_e32 v110, v133
	v_mov_b32_e32 v111, v133
	v_mov_b32_e32 v112, v133
	v_mov_b32_e32 v113, v133
	v_mov_b32_e32 v98, v133
	v_mov_b32_e32 v99, v133
	v_mov_b32_e32 v100, v133
	v_mov_b32_e32 v101, v133
	v_mov_b32_e32 v106, v133
	v_mov_b32_e32 v107, v133
	v_mov_b32_e32 v108, v133
	v_mov_b32_e32 v109, v133
	v_mov_b32_e32 v90, v133
	v_mov_b32_e32 v91, v133
	v_mov_b32_e32 v92, v133
	v_mov_b32_e32 v93, v133
	v_mov_b32_e32 v94, v133
	v_mov_b32_e32 v95, v133
	v_mov_b32_e32 v96, v133
	v_mov_b32_e32 v97, v133
	v_mov_b32_e32 v26, v133
	v_mov_b32_e32 v27, v133
	v_mov_b32_e32 v28, v133
	v_mov_b32_e32 v29, v133
	v_mov_b32_e32 v30, v133
	v_mov_b32_e32 v31, v133
	v_mov_b32_e32 v32, v133
	v_mov_b32_e32 v33, v133
	v_mov_b32_e32 v10, v133
	v_mov_b32_e32 v11, v133
	v_mov_b32_e32 v12, v133
	v_mov_b32_e32 v13, v133
	v_mov_b32_e32 v22, v133
	v_mov_b32_e32 v23, v133
	v_mov_b32_e32 v24, v133
	v_mov_b32_e32 v25, v133
	v_mov_b32_e32 v6, v133
	v_mov_b32_e32 v7, v133
	v_mov_b32_e32 v8, v133
	v_mov_b32_e32 v9, v133
	v_mov_b32_e32 v18, v133
	v_mov_b32_e32 v19, v133
	v_mov_b32_e32 v20, v133
	v_mov_b32_e32 v21, v133
	v_mov_b32_e32 v2, v133
	v_mov_b32_e32 v4, v133
	v_mov_b32_e32 v5, v133
	v_mov_b32_e32 v14, v133
	v_mov_b32_e32 v15, v133
	v_mov_b32_e32 v16, v133
	v_mov_b32_e32 v17, v133
	v_mov_b32_e32 v74, v133
	v_mov_b32_e32 v75, v133
	v_mov_b32_e32 v76, v133
	v_mov_b32_e32 v77, v133
	v_mov_b32_e32 v86, v133
	v_mov_b32_e32 v87, v133
	v_mov_b32_e32 v88, v133
	v_mov_b32_e32 v89, v133
	v_mov_b32_e32 v50, v133
	v_mov_b32_e32 v51, v133
	v_mov_b32_e32 v52, v133
	v_mov_b32_e32 v53, v133
	v_mov_b32_e32 v70, v133
	v_mov_b32_e32 v71, v133
	v_mov_b32_e32 v72, v133
	v_mov_b32_e32 v73, v133
	v_mov_b32_e32 v42, v133
	v_mov_b32_e32 v43, v133
	v_mov_b32_e32 v44, v133
	v_mov_b32_e32 v45, v133
	v_mov_b32_e32 v58, v133
	v_mov_b32_e32 v59, v133
	v_mov_b32_e32 v60, v133
	v_mov_b32_e32 v61, v133
	v_mov_b32_e32 v54, v133
	v_mov_b32_e32 v55, v133
	v_mov_b32_e32 v56, v133
	v_mov_b32_e32 v57, v133
	v_mov_b32_e32 v82, v133
	v_mov_b32_e32 v83, v133
	v_mov_b32_e32 v84, v133
	v_mov_b32_e32 v85, v133
	s_barrier
	s_cmpk_lt_u32 s26, 0x100
	s_cbranch_scc0 .Lmy_d1360B
; #define PG8_STAGE(bufoff, gbase, voff) do { _Pragma("unroll") for (int _i = 0; _i < 2; ++_i) \
;         __builtin_amdgcn_global_load_lds((const unsigned*)((const char*)(gbase) + (voff)[_i]), (LAS unsigned*)(lds + (bufoff) + ldsw + _i * 8192), 16, 0, 0); } while (0)
; #define PG8_LDA(dst, b, h) do { _Pragma("unroll") for (int m = 0; m < 4; ++m) _Pragma("unroll") for (int k = 0; k < 2; ++k) dst[m][k] = *(const LAS bf16x8*)(lds + PG8_SA(b, h) + aoff + m * 2048 + k * 1024); } while (0)
; #define PG8_LDB(dst, b, h) do { _Pragma("unroll") for (int n = 0; n < 2; ++n) _Pragma("unroll") for (int k = 0; k < 2; ++k) dst[n][k] = *(const LAS bf16x8*)(lds + PG8_SB(b, h) + boff + n * 2048 + k * 1024); } while (0)
; #define PG8_MMA(ai, bj, At, Bt) do { __builtin_amdgcn_s_setprio(1); _Pragma("unroll") for (int m = 0; m < 4; ++m) _Pragma("unroll") for (int n = 0; n < 2; ++n) _Pragma("unroll") for (int k = 0; k < 2; ++k) \
;         acc[ai][bj][m][n] = __builtin_amdgcn_mfma_f32_16x16x32_bf16(Bt[n][k], At[m][k], acc[ai][bj][m][n], 0, 0, 0); __builtin_amdgcn_s_setprio(0); } while (0)
; #define PG8_WAIT_V(n) asm volatile("s_waitcnt vmcnt(" #n ")" ::: "memory")
; #define PG8_WAIT_L(n) asm volatile("s_waitcnt lgkmcnt(" #n ")" ::: "memory")
; #define PG8_BAR __builtin_amdgcn_s_barrier()
; #define PG8_SCHED __builtin_amdgcn_sched_barrier(0)
; template <class Epi, class Sched, bool ALIGN_EPI, class Hook = NoHook>
; __device__ __forceinline__ void gemm_phase(LAS unsigned char* lds, const Gemm g, const Sched& S, const Epi& E, const Hook& H = Hook()) {
;     ...
;             PG8_LDB(B0, 0, 0); PG8_LDB(B1, 0, 1); PG8_SCHED; PG8_LDA(At, 0, 0); PG8_STAGE(PG8_SA(1, 1), a1 + hA, voffA);
;             PG8_WAIT_V(8); PG8_WAIT_L(0); PG8_BAR; PG8_MMA(0, 0, At, B0); PG8_MMA(0, 1, At, B1); PG8_BAR; PG8_SCHED;
;             PG8_LDA(At, 0, 1); PG8_STAGE(PG8_SB(0, 0), b2, voffB); PG8_STAGE(PG8_SB(0, 1), b2 + hB, voffB); PG8_STAGE(PG8_SA(0, 0), a2, voffA);
;             PG8_WAIT_V(8); PG8_WAIT_L(0); PG8_BAR; PG8_MMA(1, 0, At, B0); PG8_MMA(1, 1, At, B1); PG8_BAR; PG8_SCHED;
.LBB0_1360:
	ds_read_b128 v[146:149], v1
	ds_read_b128 v[150:153], v1 offset:1024
	s_add_u32 s14, s4, 0xbb050080
	s_addc_u32 s15, s5, -1
	s_cmpk_lg_i32 s41, 0xa8
	s_cselect_b32 s14, s14, 0
	s_cselect_b32 s15, s15, 0
	s_add_u32 s20, s0, s14
	s_addc_u32 s21, s1, s15
	s_add_u32 s14, s12, s14
	s_addc_u32 s15, s13, s15
	s_mov_b32 m0, s42
	ds_read_b128 v[154:157], v1 offset:2048
	ds_read_b128 v[158:161], v1 offset:3072
	ds_read_b128 v[164:167], v142
	ds_read_b128 v[170:173], v142 offset:1024
	ds_read_b128 v[174:177], v142 offset:2048
	ds_read_b128 v[178:181], v142 offset:3072
	v_lshl_add_u64 v[214:215], v[138:139], 0, s[4:5]
	global_load_lds_dwordx4 v[214:215], off
	ds_read_b128 v[182:185], v143
	ds_read_b128 v[186:189], v143 offset:1024
	ds_read_b128 v[190:193], v143 offset:2048
	ds_read_b128 v[194:197], v143 offset:3072
	ds_read_b128 v[198:201], v143 offset:4096
	ds_read_b128 v[202:205], v143 offset:5120
	ds_read_b128 v[206:209], v143 offset:6144
	ds_read_b128 v[210:213], v143 offset:7168
	v_lshl_add_u64 v[214:215], v[140:141], 0, s[4:5]
	s_mov_b32 m0, s43
	s_nop 0
	global_load_lds_dwordx4 v[214:215], off
	s_waitcnt lgkmcnt(0)
	s_barrier
	s_setprio 1
	s_waitcnt lgkmcnt(0)
	v_mfma_f32_16x16x32_bf16 v[82:85], v[146:149], v[182:185], v[82:85]
	v_mfma_f32_16x16x32_bf16 v[54:57], v[154:157], v[182:185], v[54:57]
	v_mfma_f32_16x16x32_bf16 v[58:61], v[146:149], v[190:193], v[58:61]
	v_mfma_f32_16x16x32_bf16 v[42:45], v[154:157], v[190:193], v[42:45]
	v_mfma_f32_16x16x32_bf16 v[70:73], v[146:149], v[198:201], v[70:73]
	v_mfma_f32_16x16x32_bf16 v[50:53], v[154:157], v[198:201], v[50:53]
	v_mfma_f32_16x16x32_bf16 v[86:89], v[146:149], v[206:209], v[86:89]
	v_mfma_f32_16x16x32_bf16 v[74:77], v[154:157], v[206:209], v[74:77]
	v_mfma_f32_16x16x32_bf16 v[82:85], v[150:153], v[186:189], v[82:85]
	v_mfma_f32_16x16x32_bf16 v[54:57], v[158:161], v[186:189], v[54:57]
	v_mfma_f32_16x16x32_bf16 v[58:61], v[150:153], v[194:197], v[58:61]
	v_mfma_f32_16x16x32_bf16 v[42:45], v[158:161], v[194:197], v[42:45]
	v_mfma_f32_16x16x32_bf16 v[70:73], v[150:153], v[202:205], v[70:73]
	v_mfma_f32_16x16x32_bf16 v[50:53], v[158:161], v[202:205], v[50:53]
	v_mfma_f32_16x16x32_bf16 v[86:89], v[150:153], v[210:213], v[86:89]
	v_mfma_f32_16x16x32_bf16 v[74:77], v[158:161], v[210:213], v[74:77]
	s_setprio 0
	s_setprio 1
	v_mfma_f32_16x16x32_bf16 v[14:17], v[164:167], v[182:185], v[14:17]
	v_mfma_f32_16x16x32_bf16 v[2:5], v[174:177], v[182:185], v[2:5]
	v_mfma_f32_16x16x32_bf16 v[18:21], v[164:167], v[190:193], v[18:21]
	v_mfma_f32_16x16x32_bf16 v[6:9], v[174:177], v[190:193], v[6:9]
	v_mfma_f32_16x16x32_bf16 v[22:25], v[164:167], v[198:201], v[22:25]
	v_mfma_f32_16x16x32_bf16 v[10:13], v[174:177], v[198:201], v[10:13]
	v_mfma_f32_16x16x32_bf16 v[30:33], v[164:167], v[206:209], v[30:33]
	v_mfma_f32_16x16x32_bf16 v[26:29], v[174:177], v[206:209], v[26:29]
	v_mfma_f32_16x16x32_bf16 v[14:17], v[170:173], v[186:189], v[14:17]
	v_mfma_f32_16x16x32_bf16 v[2:5], v[178:181], v[186:189], v[2:5]
	v_mfma_f32_16x16x32_bf16 v[18:21], v[170:173], v[194:197], v[18:21]
	v_mfma_f32_16x16x32_bf16 v[6:9], v[178:181], v[194:197], v[6:9]
	v_mfma_f32_16x16x32_bf16 v[22:25], v[170:173], v[202:205], v[22:25]
	v_mfma_f32_16x16x32_bf16 v[10:13], v[178:181], v[202:205], v[10:13]
	v_mfma_f32_16x16x32_bf16 v[30:33], v[170:173], v[210:213], v[30:33]
	v_mfma_f32_16x16x32_bf16 v[26:29], v[178:181], v[210:213], v[26:29]
	s_setprio 0
	s_waitcnt vmcnt(8)
	s_barrier
	s_mov_b32 m0, s44
	s_add_u32 s52, s14, 0x2b0000
	ds_read_b128 v[182:185], v143 offset:16384
	ds_read_b128 v[186:189], v143 offset:17408
	global_load_lds_dwordx4 v132, s[14:15]
	ds_read_b128 v[190:193], v143 offset:18432
	s_mov_b32 m0, s45
	s_addc_u32 s53, s15, 0
	global_load_lds_dwordx4 v136, s[14:15]
	ds_read_b128 v[194:197], v143 offset:19456
	s_mov_b32 m0, s46
	s_nop 0
	global_load_lds_dwordx4 v132, s[52:53]
	ds_read_b128 v[198:201], v143 offset:20480
	s_mov_b32 m0, s47
	s_nop 0
	global_load_lds_dwordx4 v136, s[52:53]
	ds_read_b128 v[202:205], v143 offset:21504
	s_add_u32 s56, s20, s2
	s_addc_u32 s57, s21, s3
	s_mov_b32 m0, s25
	s_nop 0
	global_load_lds_dwordx4 v130, s[20:21]
	ds_read_b128 v[206:209], v143 offset:22528
	s_mov_b32 m0, s27
	s_nop 0
	global_load_lds_dwordx4 v134, s[20:21]
	ds_read_b128 v[210:213], v143 offset:23552
	s_waitcnt lgkmcnt(0)
	s_barrier
	s_setprio 1
	s_waitcnt lgkmcnt(0)
	v_mfma_f32_16x16x32_bf16 v[94:97], v[146:149], v[182:185], v[94:97]
	v_mfma_f32_16x16x32_bf16 v[90:93], v[154:157], v[182:185], v[90:93]
	v_mfma_f32_16x16x32_bf16 v[106:109], v[146:149], v[190:193], v[106:109]
	v_mfma_f32_16x16x32_bf16 v[98:101], v[154:157], v[190:193], v[98:101]
	v_mfma_f32_16x16x32_bf16 v[110:113], v[146:149], v[198:201], v[110:113]
	v_mfma_f32_16x16x32_bf16 v[102:105], v[154:157], v[198:201], v[102:105]
	v_mfma_f32_16x16x32_bf16 v[126:129], v[146:149], v[206:209], v[126:129]
	v_mfma_f32_16x16x32_bf16 v[122:125], v[154:157], v[206:209], v[122:125]
	v_mfma_f32_16x16x32_bf16 v[94:97], v[150:153], v[186:189], v[94:97]
	v_mfma_f32_16x16x32_bf16 v[90:93], v[158:161], v[186:189], v[90:93]
	v_mfma_f32_16x16x32_bf16 v[106:109], v[150:153], v[194:197], v[106:109]
	v_mfma_f32_16x16x32_bf16 v[98:101], v[158:161], v[194:197], v[98:101]
	v_mfma_f32_16x16x32_bf16 v[110:113], v[150:153], v[202:205], v[110:113]
	v_mfma_f32_16x16x32_bf16 v[102:105], v[158:161], v[202:205], v[102:105]
	v_mfma_f32_16x16x32_bf16 v[126:129], v[150:153], v[210:213], v[126:129]
	v_mfma_f32_16x16x32_bf16 v[122:125], v[158:161], v[210:213], v[122:125]
	s_setprio 0
	s_setprio 1
	v_mfma_f32_16x16x32_bf16 v[38:41], v[164:167], v[182:185], v[38:41]
	v_mfma_f32_16x16x32_bf16 v[34:37], v[174:177], v[182:185], v[34:37]
	v_mfma_f32_16x16x32_bf16 v[66:69], v[164:167], v[190:193], v[66:69]
	v_mfma_f32_16x16x32_bf16 v[46:49], v[174:177], v[190:193], v[46:49]
	v_mfma_f32_16x16x32_bf16 v[78:81], v[164:167], v[198:201], v[78:81]
	v_mfma_f32_16x16x32_bf16 v[62:65], v[174:177], v[198:201], v[62:65]
	v_mfma_f32_16x16x32_bf16 v[118:121], v[164:167], v[206:209], v[118:121]
	v_mfma_f32_16x16x32_bf16 v[114:117], v[174:177], v[206:209], v[114:117]
	v_mfma_f32_16x16x32_bf16 v[38:41], v[170:173], v[186:189], v[38:41]
	v_mfma_f32_16x16x32_bf16 v[34:37], v[178:181], v[186:189], v[34:37]
	v_mfma_f32_16x16x32_bf16 v[66:69], v[170:173], v[194:197], v[66:69]
	v_mfma_f32_16x16x32_bf16 v[46:49], v[178:181], v[194:197], v[46:49]
	v_mfma_f32_16x16x32_bf16 v[78:81], v[170:173], v[202:205], v[78:81]
	v_mfma_f32_16x16x32_bf16 v[62:65], v[178:181], v[202:205], v[62:65]
	v_mfma_f32_16x16x32_bf16 v[118:121], v[170:173], v[210:213], v[118:121]
	v_mfma_f32_16x16x32_bf16 v[114:117], v[178:181], v[210:213], v[114:117]
	s_setprio 0
	s_waitcnt vmcnt(8)
	s_barrier
; #define PG8_STAGE(bufoff, gbase, voff) do { _Pragma("unroll") for (int _i = 0; _i < 2; ++_i) \
;         __builtin_amdgcn_global_load_lds((const unsigned*)((const char*)(gbase) + (voff)[_i]), (LAS unsigned*)(lds + (bufoff) + ldsw + _i * 8192), 16, 0, 0); } while (0)
; #define PG8_LDA(dst, b, h) do { _Pragma("unroll") for (int m = 0; m < 4; ++m) _Pragma("unroll") for (int k = 0; k < 2; ++k) dst[m][k] = *(const LAS bf16x8*)(lds + PG8_SA(b, h) + aoff + m * 2048 + k * 1024); } while (0)
; #define PG8_LDB(dst, b, h) do { _Pragma("unroll") for (int n = 0; n < 2; ++n) _Pragma("unroll") for (int k = 0; k < 2; ++k) dst[n][k] = *(const LAS bf16x8*)(lds + PG8_SB(b, h) + boff + n * 2048 + k * 1024); } while (0)
; #define PG8_MMA(ai, bj, At, Bt) do { __builtin_amdgcn_s_setprio(1); _Pragma("unroll") for (int m = 0; m < 4; ++m) _Pragma("unroll") for (int n = 0; n < 2; ++n) _Pragma("unroll") for (int k = 0; k < 2; ++k) \
;         acc[ai][bj][m][n] = __builtin_amdgcn_mfma_f32_16x16x32_bf16(Bt[n][k], At[m][k], acc[ai][bj][m][n], 0, 0, 0); __builtin_amdgcn_s_setprio(0); } while (0)
; #define PG8_WAIT_V(n) asm volatile("s_waitcnt vmcnt(" #n ")" ::: "memory")
; #define PG8_WAIT_L(n) asm volatile("s_waitcnt lgkmcnt(" #n ")" ::: "memory")
; #define PG8_BAR __builtin_amdgcn_s_barrier()
; #define PG8_SCHED __builtin_amdgcn_sched_barrier(0)
; template <class Epi, class Sched, bool ALIGN_EPI, class Hook = NoHook>
; __device__ __forceinline__ void gemm_phase(LAS unsigned char* lds, const Gemm g, const Sched& S, const Epi& E, const Hook& H = Hook()) {
;     ...
;             PG8_LDB(B0, 1, 0); PG8_LDB(B1, 1, 1); PG8_SCHED; PG8_LDA(At, 1, 0); PG8_STAGE(PG8_SA(0, 1), a2 + hA, voffA);
;             PG8_WAIT_V(8); PG8_WAIT_L(0); PG8_BAR; PG8_MMA(0, 0, At, B0); PG8_MMA(0, 1, At, B1); PG8_BAR; PG8_SCHED;
;             PG8_LDA(At, 1, 1); PG8_STAGE(PG8_SB(1, 0), b3, voffB); PG8_STAGE(PG8_SB(1, 1), b3 + hB, voffB); PG8_STAGE(PG8_SA(1, 0), a3, voffA);
;             PG8_WAIT_V(8); PG8_WAIT_L(0); PG8_BAR; PG8_MMA(1, 0, At, B0); PG8_MMA(1, 1, At, B1); PG8_BAR; PG8_SCHED;
;         }
	ds_read_b128 v[146:149], v144
	ds_read_b128 v[150:153], v144 offset:1024
	s_add_u32 s20, s20, 0x2b0000
	s_addc_u32 s21, s21, 0
	s_mov_b32 m0, s28
	s_nop 0
	global_load_lds_dwordx4 v130, s[20:21]
	ds_read_b128 v[154:157], v144 offset:2048
	ds_read_b128 v[158:161], v144 offset:3072
	ds_read_b128 v[164:167], v145
	ds_read_b128 v[170:173], v145 offset:1024
	ds_read_b128 v[174:177], v145 offset:2048
	ds_read_b128 v[178:181], v145 offset:3072
	ds_read_b128 v[182:185], v143 offset:32768
	s_mov_b32 m0, s38
	s_nop 0
	global_load_lds_dwordx4 v134, s[20:21]
	ds_read_b128 v[186:189], v143 offset:33792
	ds_read_b128 v[190:193], v143 offset:34816
	ds_read_b128 v[194:197], v143 offset:35840
	ds_read_b128 v[198:201], v143 offset:36864
	ds_read_b128 v[202:205], v143 offset:37888
	ds_read_b128 v[206:209], v143 offset:38912
	ds_read_b128 v[210:213], v143 offset:39936
	s_waitcnt lgkmcnt(0)
	s_barrier
	s_setprio 1
	s_waitcnt lgkmcnt(0)
	v_mfma_f32_16x16x32_bf16 v[82:85], v[146:149], v[182:185], v[82:85]
	v_mfma_f32_16x16x32_bf16 v[54:57], v[154:157], v[182:185], v[54:57]
	v_mfma_f32_16x16x32_bf16 v[58:61], v[146:149], v[190:193], v[58:61]
	v_mfma_f32_16x16x32_bf16 v[42:45], v[154:157], v[190:193], v[42:45]
	v_mfma_f32_16x16x32_bf16 v[70:73], v[146:149], v[198:201], v[70:73]
	v_mfma_f32_16x16x32_bf16 v[50:53], v[154:157], v[198:201], v[50:53]
	v_mfma_f32_16x16x32_bf16 v[86:89], v[146:149], v[206:209], v[86:89]
	v_mfma_f32_16x16x32_bf16 v[74:77], v[154:157], v[206:209], v[74:77]
	v_mfma_f32_16x16x32_bf16 v[82:85], v[150:153], v[186:189], v[82:85]
	v_mfma_f32_16x16x32_bf16 v[54:57], v[158:161], v[186:189], v[54:57]
	v_mfma_f32_16x16x32_bf16 v[58:61], v[150:153], v[194:197], v[58:61]
	v_mfma_f32_16x16x32_bf16 v[42:45], v[158:161], v[194:197], v[42:45]
	v_mfma_f32_16x16x32_bf16 v[70:73], v[150:153], v[202:205], v[70:73]
	v_mfma_f32_16x16x32_bf16 v[50:53], v[158:161], v[202:205], v[50:53]
	v_mfma_f32_16x16x32_bf16 v[86:89], v[150:153], v[210:213], v[86:89]
	v_mfma_f32_16x16x32_bf16 v[74:77], v[158:161], v[210:213], v[74:77]
	s_setprio 0
	s_setprio 1
	v_mfma_f32_16x16x32_bf16 v[14:17], v[164:167], v[182:185], v[14:17]
	v_mfma_f32_16x16x32_bf16 v[2:5], v[174:177], v[182:185], v[2:5]
	v_mfma_f32_16x16x32_bf16 v[18:21], v[164:167], v[190:193], v[18:21]
	v_mfma_f32_16x16x32_bf16 v[6:9], v[174:177], v[190:193], v[6:9]
	v_mfma_f32_16x16x32_bf16 v[22:25], v[164:167], v[198:201], v[22:25]
	v_mfma_f32_16x16x32_bf16 v[10:13], v[174:177], v[198:201], v[10:13]
	v_mfma_f32_16x16x32_bf16 v[30:33], v[164:167], v[206:209], v[30:33]
	v_mfma_f32_16x16x32_bf16 v[26:29], v[174:177], v[206:209], v[26:29]
	v_mfma_f32_16x16x32_bf16 v[14:17], v[170:173], v[186:189], v[14:17]
	v_mfma_f32_16x16x32_bf16 v[2:5], v[178:181], v[186:189], v[2:5]
	v_mfma_f32_16x16x32_bf16 v[18:21], v[170:173], v[194:197], v[18:21]
	v_mfma_f32_16x16x32_bf16 v[6:9], v[178:181], v[194:197], v[6:9]
	v_mfma_f32_16x16x32_bf16 v[22:25], v[170:173], v[202:205], v[22:25]
	v_mfma_f32_16x16x32_bf16 v[10:13], v[178:181], v[202:205], v[10:13]
	v_mfma_f32_16x16x32_bf16 v[30:33], v[170:173], v[210:213], v[30:33]
	v_mfma_f32_16x16x32_bf16 v[26:29], v[178:181], v[210:213], v[26:29]
	s_setprio 0
	s_waitcnt vmcnt(8)
	s_barrier
	s_mov_b32 m0, s48
	s_add_u32 s54, s14, s2
	s_addc_u32 s55, s15, s3
	s_add_u32 s14, s14, 0x2b0080
	ds_read_b128 v[182:185], v143 offset:49152
	ds_read_b128 v[186:189], v143 offset:50176
	global_load_lds_dwordx4 v132, s[54:55]
	ds_read_b128 v[190:193], v143 offset:51200
	s_mov_b32 m0, s49
	s_addc_u32 s15, s15, 0
	global_load_lds_dwordx4 v136, s[54:55]
	ds_read_b128 v[194:197], v143 offset:52224
	s_mov_b32 m0, s50
	s_nop 0
	global_load_lds_dwordx4 v132, s[14:15]
	ds_read_b128 v[198:201], v143 offset:53248
	s_mov_b32 m0, s51
	s_nop 0
	global_load_lds_dwordx4 v136, s[14:15]
	ds_read_b128 v[202:205], v143 offset:54272
	s_mov_b32 m0, s39
	s_nop 0
	global_load_lds_dwordx4 v130, s[56:57]
	ds_read_b128 v[206:209], v143 offset:55296
	s_mov_b32 m0, s40
	s_nop 0
	global_load_lds_dwordx4 v134, s[56:57]
	ds_read_b128 v[210:213], v143 offset:56320
	s_waitcnt lgkmcnt(0)
	s_barrier
	s_setprio 1
	s_waitcnt lgkmcnt(0)
	v_mfma_f32_16x16x32_bf16 v[94:97], v[146:149], v[182:185], v[94:97]
	v_mfma_f32_16x16x32_bf16 v[90:93], v[154:157], v[182:185], v[90:93]
	v_mfma_f32_16x16x32_bf16 v[106:109], v[146:149], v[190:193], v[106:109]
	v_mfma_f32_16x16x32_bf16 v[98:101], v[154:157], v[190:193], v[98:101]
	v_mfma_f32_16x16x32_bf16 v[110:113], v[146:149], v[198:201], v[110:113]
	v_mfma_f32_16x16x32_bf16 v[102:105], v[154:157], v[198:201], v[102:105]
	v_mfma_f32_16x16x32_bf16 v[126:129], v[146:149], v[206:209], v[126:129]
	v_mfma_f32_16x16x32_bf16 v[122:125], v[154:157], v[206:209], v[122:125]
	v_mfma_f32_16x16x32_bf16 v[94:97], v[150:153], v[186:189], v[94:97]
	v_mfma_f32_16x16x32_bf16 v[90:93], v[158:161], v[186:189], v[90:93]
	v_mfma_f32_16x16x32_bf16 v[106:109], v[150:153], v[194:197], v[106:109]
	v_mfma_f32_16x16x32_bf16 v[98:101], v[158:161], v[194:197], v[98:101]
	v_mfma_f32_16x16x32_bf16 v[110:113], v[150:153], v[202:205], v[110:113]
	v_mfma_f32_16x16x32_bf16 v[102:105], v[158:161], v[202:205], v[102:105]
	v_mfma_f32_16x16x32_bf16 v[126:129], v[150:153], v[210:213], v[126:129]
	v_mfma_f32_16x16x32_bf16 v[122:125], v[158:161], v[210:213], v[122:125]
	s_setprio 0
	s_setprio 1
	v_mfma_f32_16x16x32_bf16 v[38:41], v[164:167], v[182:185], v[38:41]
	v_mfma_f32_16x16x32_bf16 v[34:37], v[174:177], v[182:185], v[34:37]
	v_mfma_f32_16x16x32_bf16 v[66:69], v[164:167], v[190:193], v[66:69]
	v_mfma_f32_16x16x32_bf16 v[46:49], v[174:177], v[190:193], v[46:49]
	v_mfma_f32_16x16x32_bf16 v[78:81], v[164:167], v[198:201], v[78:81]
	v_mfma_f32_16x16x32_bf16 v[62:65], v[174:177], v[198:201], v[62:65]
	v_mfma_f32_16x16x32_bf16 v[118:121], v[164:167], v[206:209], v[118:121]
	v_mfma_f32_16x16x32_bf16 v[114:117], v[174:177], v[206:209], v[114:117]
	v_mfma_f32_16x16x32_bf16 v[38:41], v[170:173], v[186:189], v[38:41]
	v_mfma_f32_16x16x32_bf16 v[34:37], v[178:181], v[186:189], v[34:37]
	v_mfma_f32_16x16x32_bf16 v[66:69], v[170:173], v[194:197], v[66:69]
	v_mfma_f32_16x16x32_bf16 v[46:49], v[178:181], v[194:197], v[46:49]
	v_mfma_f32_16x16x32_bf16 v[78:81], v[170:173], v[202:205], v[78:81]
	v_mfma_f32_16x16x32_bf16 v[62:65], v[178:181], v[202:205], v[62:65]
	v_mfma_f32_16x16x32_bf16 v[118:121], v[170:173], v[210:213], v[118:121]
	v_mfma_f32_16x16x32_bf16 v[114:117], v[178:181], v[210:213], v[114:117]
	s_setprio 0
	s_waitcnt vmcnt(8)
	s_barrier
	s_add_i32 s41, s41, 2
	s_add_u32 s4, s4, 0x100
	s_addc_u32 s5, s5, 0
	s_cmpk_gt_u32 s41, 0xa9
	s_cbranch_scc0 .LBB0_1360
	s_branch .Lmy_d1360X

; #define PG8_STAGE(bufoff, gbase, voff) do { _Pragma("unroll") for (int _i = 0; _i < 2; ++_i) \
;         __builtin_amdgcn_global_load_lds((const unsigned*)((const char*)(gbase) + (voff)[_i]), (LAS unsigned*)(lds + (bufoff) + ldsw + _i * 8192), 16, 0, 0); } while (0)
; #define PG8_WAIT_V(n) asm volatile("s_waitcnt vmcnt(" #n ")" ::: "memory")
; #define PG8_BAR __builtin_amdgcn_s_barrier()
; template <class Epi, class Sched, bool ALIGN_EPI, class Hook = NoHook>
; __device__ __forceinline__ void gemm_phase(LAS unsigned char* lds, const Gemm g, const Sched& S, const Epi& E, const Hook& H = Hook()) {
;     ...
;     f32x4 acc[2][2][4][2];
; #pragma unroll
;     for (int a = 0; a < 2; ++a)
; #pragma unroll
;         for (int b = 0; b < 2; ++b)
; #pragma unroll
;             for (int m = 0; m < 4; ++m)
; #pragma unroll
;                 for (int n = 0; n < 2; ++n) acc[a][b][m][n] = (f32x4){0.f, 0.f, 0.f, 0.f};
;     bf16x8 At[4][2], B0[2][2], B1[2][2];
;     const char* cA = (const char*)g.A + (size_t)cur.pm * tA + (size_t)cur.ka * 2; const char* cB = (const char*)g.Bt + (size_t)cur.pn * 2 * hB + (size_t)cur.ka * 2;
;     S.a_ready(cur);
;     if constexpr (Hook::ON) H.unit_start(cur);
;     PG8_STAGE(PG8_SB(0, 0), cB, voffB); PG8_STAGE(PG8_SB(0, 1), cB + hB, voffB); PG8_STAGE(PG8_SA(0, 0), cA, voffA); PG8_STAGE(PG8_SA(0, 1), cA + hA, voffA);
;     if (wr == 1) PG8_BAR;
;     PG8_WAIT_V(2); PG8_BAR;
;     PG8_STAGE(PG8_SB(1, 0), cB + kstep, voffB); PG8_STAGE(PG8_SA(1, 0), cA + kstep, voffA); PG8_STAGE(PG8_SB(1, 1), cB + hB + kstep, voffB);
;     PG8_WAIT_V(6); PG8_BAR;
.LBB0_1405:
	v_and_b32_e32 v164, 15, v0
	v_and_b32_e32 v18, 48, v0
	v_lshlrev_b32_e32 v19, 2, v0
	s_and_b32 s25, s23, 3
	s_lshl_b32 s2, s24, 13
	v_lshl_or_b32 v18, v164, 6, v18
	v_and_b32_e32 v19, 32, v19
	v_bitop3_b32 v20, v18, s2, v19 bitop3:0xde
	s_lshl_b32 s2, s25, 12
	v_bitop3_b32 v18, v18, s2, v19 bitop3:0xde
	s_mov_b64 s[2:3], 0x80
	s_add_i32 m0, s27, 0x18000
	v_lshl_add_u64 v[8:9], v[8:9], 0, s[2:3]
	s_waitcnt vmcnt(2)
	s_barrier
	global_load_lds_dwordx4 v[8:9], off
	v_lshl_add_u64 v[6:7], v[6:7], 0, s[2:3]
	s_add_i32 m0, s27, 0x1a000
	s_add_i32 s41, s27, 0x8000
	global_load_lds_dwordx4 v[6:7], off
	v_lshl_add_u64 v[4:5], v[4:5], 0, s[2:3]
	s_mov_b32 m0, s41
	s_add_i32 s42, s27, 0xa000
	global_load_lds_dwordx4 v[4:5], off
	v_lshl_add_u64 v[2:3], v[2:3], 0, s[2:3]
	s_mov_b32 m0, s42
	s_add_i32 s5, s31, s33
	global_load_lds_dwordx4 v[2:3], off
	s_add_i32 m0, s27, 0x1c000
	v_lshl_add_u64 v[2:3], s[18:19], 0, v[162:163]
	global_load_lds_dwordx4 v[2:3], off
	v_lshl_add_u64 v[2:3], s[18:19], 0, v[134:135]
	s_add_i32 m0, s27, 0x1e000
	s_mul_i32 s5, s5, 0x560000
	global_load_lds_dwordx4 v[2:3], off
	v_lshrrev_b32_e32 v3, 1, v10
	v_mul_lo_u32 v2, v12, s4
	s_mov_b32 s16, 0x2b000
	s_lshl_b32 s40, s24, 6
	s_add_i32 s5, s5, 0x5600000
	v_mad_u64_u32 v[2:3], s[10:11], v3, s16, v[2:3]
	v_or_b32_e32 v2, v2, v11
	s_add_u32 s10, s96, s5
	v_add_lshl_u32 v2, v2, v13, 1
	v_mov_b32_e32 v3, v163
	s_addc_u32 s11, s97, 0
	v_lshl_add_u64 v[136:137], s[10:11], 0, v[2:3]
	v_lshrrev_b32_e32 v3, 1, v14
	v_mul_lo_u32 v2, v15, s4
	v_mad_u64_u32 v[2:3], s[4:5], v3, s16, v[2:3]
	s_waitcnt vmcnt(6)
	v_or_b32_e32 v2, v2, v16
	v_add_lshl_u32 v2, v2, v17, 1
	v_mov_b32_e32 v3, v163
	v_add_u32_e32 v141, s35, v18
	s_add_i32 s33, s34, s45
	s_add_i32 s35, s35, s45
	v_add_u32_e32 v143, s36, v18
	v_add_u32_e32 v144, s37, v18
	s_add_i32 s36, s36, s45
	s_add_i32 s37, s37, s45
	v_or_b32_e32 v166, s40, v164
	v_lshl_add_u64 v[138:139], s[10:11], 0, v[2:3]
	s_mov_b32 s18, -2
	s_mov_b64 s[4:5], 0x44fb0080
	v_add_u32_e32 v140, s34, v18
	v_add_u32_e32 v142, 0, v20
	s_add_i32 s19, s27, 0xc000
	s_add_i32 s31, s27, 0xe000
	s_add_i32 s34, s33, 0x2000
	s_add_i32 s43, s35, 0x2000
	s_add_i32 s44, s36, 0x2000
	s_add_i32 s45, s37, 0x2000
	v_mov_b32_e32 v102, v163
	v_mov_b32_e32 v103, v163
	v_mov_b32_e32 v104, v163
	v_mov_b32_e32 v105, v163
	v_mov_b32_e32 v106, v163
	v_mov_b32_e32 v107, v163
	v_mov_b32_e32 v108, v163
	v_mov_b32_e32 v109, v163
	v_mov_b32_e32 v62, v163
	v_mov_b32_e32 v63, v163
	v_mov_b32_e32 v64, v163
	v_mov_b32_e32 v65, v163
	v_mov_b32_e32 v78, v163
	v_mov_b32_e32 v79, v163
	v_mov_b32_e32 v80, v163
	v_mov_b32_e32 v81, v163
	v_mov_b32_e32 v46, v163
	v_mov_b32_e32 v47, v163
	v_mov_b32_e32 v48, v163
	v_mov_b32_e32 v49, v163
	v_mov_b32_e32 v66, v163
	v_mov_b32_e32 v67, v163
	v_mov_b32_e32 v68, v163
	v_mov_b32_e32 v69, v163
	v_mov_b32_e32 v34, v163
	v_mov_b32_e32 v35, v163
	v_mov_b32_e32 v36, v163
	v_mov_b32_e32 v37, v163
	v_mov_b32_e32 v38, v163
	v_mov_b32_e32 v39, v163
	v_mov_b32_e32 v40, v163
	v_mov_b32_e32 v41, v163
	v_mov_b32_e32 v114, v163
	v_mov_b32_e32 v115, v163
	v_mov_b32_e32 v116, v163
	v_mov_b32_e32 v117, v163
	v_mov_b32_e32 v122, v163
	v_mov_b32_e32 v123, v163
	v_mov_b32_e32 v124, v163
	v_mov_b32_e32 v125, v163
	v_mov_b32_e32 v110, v163
	v_mov_b32_e32 v111, v163
	v_mov_b32_e32 v112, v163
	v_mov_b32_e32 v113, v163
	v_mov_b32_e32 v126, v163
	v_mov_b32_e32 v127, v163
	v_mov_b32_e32 v128, v163
	v_mov_b32_e32 v129, v163
	v_mov_b32_e32 v98, v163
	v_mov_b32_e32 v99, v163
	v_mov_b32_e32 v100, v163
	v_mov_b32_e32 v101, v163
	v_mov_b32_e32 v118, v163
	v_mov_b32_e32 v119, v163
	v_mov_b32_e32 v120, v163
	v_mov_b32_e32 v121, v163
	v_mov_b32_e32 v90, v163
	v_mov_b32_e32 v91, v163
	v_mov_b32_e32 v92, v163
	v_mov_b32_e32 v93, v163
	v_mov_b32_e32 v94, v163
	v_mov_b32_e32 v95, v163
	v_mov_b32_e32 v96, v163
	v_mov_b32_e32 v97, v163
	v_mov_b32_e32 v26, v163
	v_mov_b32_e32 v27, v163
	v_mov_b32_e32 v28, v163
	v_mov_b32_e32 v29, v163
	v_mov_b32_e32 v30, v163
	v_mov_b32_e32 v31, v163
	v_mov_b32_e32 v32, v163
	v_mov_b32_e32 v33, v163
	v_mov_b32_e32 v10, v163
	v_mov_b32_e32 v11, v163
	v_mov_b32_e32 v12, v163
	v_mov_b32_e32 v13, v163
	v_mov_b32_e32 v22, v163
	v_mov_b32_e32 v23, v163
	v_mov_b32_e32 v24, v163
	v_mov_b32_e32 v25, v163
	v_mov_b32_e32 v6, v163
	v_mov_b32_e32 v7, v163
	v_mov_b32_e32 v8, v163
	v_mov_b32_e32 v9, v163
	v_mov_b32_e32 v18, v163
	v_mov_b32_e32 v19, v163
	v_mov_b32_e32 v20, v163
	v_mov_b32_e32 v21, v163
	v_mov_b32_e32 v2, v163
	v_mov_b32_e32 v4, v163
	v_mov_b32_e32 v5, v163
	v_mov_b32_e32 v14, v163
	v_mov_b32_e32 v15, v163
	v_mov_b32_e32 v16, v163
	v_mov_b32_e32 v17, v163
	v_mov_b32_e32 v74, v163
	v_mov_b32_e32 v75, v163
	v_mov_b32_e32 v76, v163
	v_mov_b32_e32 v77, v163
	v_mov_b32_e32 v86, v163
	v_mov_b32_e32 v87, v163
	v_mov_b32_e32 v88, v163
	v_mov_b32_e32 v89, v163
	v_mov_b32_e32 v50, v163
	v_mov_b32_e32 v51, v163
	v_mov_b32_e32 v52, v163
	v_mov_b32_e32 v53, v163
	v_mov_b32_e32 v70, v163
	v_mov_b32_e32 v71, v163
	v_mov_b32_e32 v72, v163
	v_mov_b32_e32 v73, v163
	v_mov_b32_e32 v42, v163
	v_mov_b32_e32 v43, v163
	v_mov_b32_e32 v44, v163
	v_mov_b32_e32 v45, v163
	v_mov_b32_e32 v58, v163
	v_mov_b32_e32 v59, v163
	v_mov_b32_e32 v60, v163
	v_mov_b32_e32 v61, v163
	v_mov_b32_e32 v54, v163
	v_mov_b32_e32 v55, v163
	v_mov_b32_e32 v56, v163
	v_mov_b32_e32 v57, v163
	v_mov_b32_e32 v82, v163
	v_mov_b32_e32 v83, v163
	v_mov_b32_e32 v84, v163
	v_mov_b32_e32 v85, v163
	s_barrier
	s_cmpk_lt_u32 s22, 0x100
	s_cbranch_scc0 .Lmy_d1406B
; #define PG8_STAGE(bufoff, gbase, voff) do { _Pragma("unroll") for (int _i = 0; _i < 2; ++_i) \
;         __builtin_amdgcn_global_load_lds((const unsigned*)((const char*)(gbase) + (voff)[_i]), (LAS unsigned*)(lds + (bufoff) + ldsw + _i * 8192), 16, 0, 0); } while (0)
; #define PG8_LDA(dst, b, h) do { _Pragma("unroll") for (int m = 0; m < 4; ++m) _Pragma("unroll") for (int k = 0; k < 2; ++k) dst[m][k] = *(const LAS bf16x8*)(lds + PG8_SA(b, h) + aoff + m * 2048 + k * 1024); } while (0)
; #define PG8_LDB(dst, b, h) do { _Pragma("unroll") for (int n = 0; n < 2; ++n) _Pragma("unroll") for (int k = 0; k < 2; ++k) dst[n][k] = *(const LAS bf16x8*)(lds + PG8_SB(b, h) + boff + n * 2048 + k * 1024); } while (0)
; #define PG8_MMA(ai, bj, At, Bt) do { __builtin_amdgcn_s_setprio(1); _Pragma("unroll") for (int m = 0; m < 4; ++m) _Pragma("unroll") for (int n = 0; n < 2; ++n) _Pragma("unroll") for (int k = 0; k < 2; ++k) \
;         acc[ai][bj][m][n] = __builtin_amdgcn_mfma_f32_16x16x32_bf16(Bt[n][k], At[m][k], acc[ai][bj][m][n], 0, 0, 0); __builtin_amdgcn_s_setprio(0); } while (0)
; #define PG8_WAIT_V(n) asm volatile("s_waitcnt vmcnt(" #n ")" ::: "memory")
; #define PG8_WAIT_L(n) asm volatile("s_waitcnt lgkmcnt(" #n ")" ::: "memory")
; #define PG8_BAR __builtin_amdgcn_s_barrier()
; #define PG8_SCHED __builtin_amdgcn_sched_barrier(0)
; template <class Epi, class Sched, bool ALIGN_EPI, class Hook = NoHook>
; __device__ __forceinline__ void gemm_phase(LAS unsigned char* lds, const Gemm g, const Sched& S, const Epi& E, const Hook& H = Hook()) {
;     ...
;             PG8_LDB(B0, 0, 0); PG8_LDB(B1, 0, 1); PG8_SCHED; PG8_LDA(At, 0, 0); PG8_STAGE(PG8_SA(1, 1), a1 + hA, voffA);
;             PG8_WAIT_V(8); PG8_WAIT_L(0); PG8_BAR; PG8_MMA(0, 0, At, B0); PG8_MMA(0, 1, At, B1); PG8_BAR; PG8_SCHED;
;             PG8_LDA(At, 0, 1); PG8_STAGE(PG8_SB(0, 0), b2, voffB); PG8_STAGE(PG8_SB(0, 1), b2 + hB, voffB); PG8_STAGE(PG8_SA(0, 0), a2, voffA);
;             PG8_WAIT_V(8); PG8_WAIT_L(0); PG8_BAR; PG8_MMA(1, 0, At, B0); PG8_MMA(1, 1, At, B1); PG8_BAR; PG8_SCHED;
.LBB0_1406:
	ds_read_b128 v[146:149], v140
	ds_read_b128 v[150:153], v140 offset:1024
	s_add_u32 s10, s4, 0xbb050080
	s_addc_u32 s11, s5, -1
	s_cmpk_lg_i32 s18, 0xa8
	s_cselect_b32 s10, s10, 0
	s_cselect_b32 s11, s11, 0
	s_add_u32 s16, s0, s10
	s_addc_u32 s17, s1, s11
	s_add_u32 s10, s12, s10
	s_addc_u32 s11, s13, s11
	s_mov_b32 m0, s19
	ds_read_b128 v[154:157], v140 offset:2048
	ds_read_b128 v[158:161], v140 offset:3072
	ds_read_b128 v[170:173], v141
	ds_read_b128 v[174:177], v141 offset:1024
	ds_read_b128 v[178:181], v141 offset:2048
	ds_read_b128 v[182:185], v141 offset:3072
	v_lshl_add_u64 v[218:219], v[136:137], 0, s[4:5]
	global_load_lds_dwordx4 v[218:219], off
	ds_read_b128 v[186:189], v142
	ds_read_b128 v[190:193], v142 offset:1024
	ds_read_b128 v[194:197], v142 offset:2048
	ds_read_b128 v[198:201], v142 offset:3072
	ds_read_b128 v[202:205], v142 offset:4096
	ds_read_b128 v[206:209], v142 offset:5120
	ds_read_b128 v[210:213], v142 offset:6144
	ds_read_b128 v[214:217], v142 offset:7168
	v_lshl_add_u64 v[218:219], v[138:139], 0, s[4:5]
	s_mov_b32 m0, s31
	s_nop 0
	global_load_lds_dwordx4 v[218:219], off
	s_waitcnt lgkmcnt(0)
	s_barrier
	s_setprio 1
	s_waitcnt lgkmcnt(0)
	v_mfma_f32_16x16x32_bf16 v[82:85], v[146:149], v[186:189], v[82:85]
	v_mfma_f32_16x16x32_bf16 v[54:57], v[154:157], v[186:189], v[54:57]
	v_mfma_f32_16x16x32_bf16 v[58:61], v[146:149], v[194:197], v[58:61]
	v_mfma_f32_16x16x32_bf16 v[42:45], v[154:157], v[194:197], v[42:45]
	v_mfma_f32_16x16x32_bf16 v[70:73], v[146:149], v[202:205], v[70:73]
	v_mfma_f32_16x16x32_bf16 v[50:53], v[154:157], v[202:205], v[50:53]
	v_mfma_f32_16x16x32_bf16 v[86:89], v[146:149], v[210:213], v[86:89]
	v_mfma_f32_16x16x32_bf16 v[74:77], v[154:157], v[210:213], v[74:77]
	v_mfma_f32_16x16x32_bf16 v[82:85], v[150:153], v[190:193], v[82:85]
	v_mfma_f32_16x16x32_bf16 v[54:57], v[158:161], v[190:193], v[54:57]
	v_mfma_f32_16x16x32_bf16 v[58:61], v[150:153], v[198:201], v[58:61]
	v_mfma_f32_16x16x32_bf16 v[42:45], v[158:161], v[198:201], v[42:45]
	v_mfma_f32_16x16x32_bf16 v[70:73], v[150:153], v[206:209], v[70:73]
	v_mfma_f32_16x16x32_bf16 v[50:53], v[158:161], v[206:209], v[50:53]
	v_mfma_f32_16x16x32_bf16 v[86:89], v[150:153], v[214:217], v[86:89]
	v_mfma_f32_16x16x32_bf16 v[74:77], v[158:161], v[214:217], v[74:77]
	s_setprio 0
	s_setprio 1
	v_mfma_f32_16x16x32_bf16 v[14:17], v[170:173], v[186:189], v[14:17]
	v_mfma_f32_16x16x32_bf16 v[2:5], v[178:181], v[186:189], v[2:5]
	v_mfma_f32_16x16x32_bf16 v[18:21], v[170:173], v[194:197], v[18:21]
	v_mfma_f32_16x16x32_bf16 v[6:9], v[178:181], v[194:197], v[6:9]
	v_mfma_f32_16x16x32_bf16 v[22:25], v[170:173], v[202:205], v[22:25]
	v_mfma_f32_16x16x32_bf16 v[10:13], v[178:181], v[202:205], v[10:13]
	v_mfma_f32_16x16x32_bf16 v[30:33], v[170:173], v[210:213], v[30:33]
	v_mfma_f32_16x16x32_bf16 v[26:29], v[178:181], v[210:213], v[26:29]
	v_mfma_f32_16x16x32_bf16 v[14:17], v[174:177], v[190:193], v[14:17]
	v_mfma_f32_16x16x32_bf16 v[2:5], v[182:185], v[190:193], v[2:5]
	v_mfma_f32_16x16x32_bf16 v[18:21], v[174:177], v[198:201], v[18:21]
	v_mfma_f32_16x16x32_bf16 v[6:9], v[182:185], v[198:201], v[6:9]
	v_mfma_f32_16x16x32_bf16 v[22:25], v[174:177], v[206:209], v[22:25]
	v_mfma_f32_16x16x32_bf16 v[10:13], v[182:185], v[206:209], v[10:13]
	v_mfma_f32_16x16x32_bf16 v[30:33], v[174:177], v[214:217], v[30:33]
	v_mfma_f32_16x16x32_bf16 v[26:29], v[182:185], v[214:217], v[26:29]
	s_setprio 0
	s_waitcnt vmcnt(8)
	s_barrier
	s_mov_b32 m0, s33
	s_add_u32 s46, s10, 0x2b0000
	ds_read_b128 v[186:189], v142 offset:16384
	ds_read_b128 v[190:193], v142 offset:17408
	global_load_lds_dwordx4 v162, s[10:11]
	ds_read_b128 v[194:197], v142 offset:18432
	s_mov_b32 m0, s34
	s_addc_u32 s47, s11, 0
	global_load_lds_dwordx4 v134, s[10:11]
	ds_read_b128 v[198:201], v142 offset:19456
	s_mov_b32 m0, s35
	s_nop 0
	global_load_lds_dwordx4 v162, s[46:47]
	ds_read_b128 v[202:205], v142 offset:20480
	s_mov_b32 m0, s43
	s_nop 0
	global_load_lds_dwordx4 v134, s[46:47]
	ds_read_b128 v[206:209], v142 offset:21504
	s_add_u32 s54, s16, s2
	s_addc_u32 s55, s17, s3
	s_mov_b32 m0, s27
	s_nop 0
	global_load_lds_dwordx4 v130, s[16:17]
	ds_read_b128 v[210:213], v142 offset:22528
	s_mov_b32 m0, s28
	s_nop 0
	global_load_lds_dwordx4 v132, s[16:17]
	ds_read_b128 v[214:217], v142 offset:23552
	s_waitcnt lgkmcnt(0)
	s_barrier
	s_setprio 1
	s_waitcnt lgkmcnt(0)
	v_mfma_f32_16x16x32_bf16 v[94:97], v[146:149], v[186:189], v[94:97]
	v_mfma_f32_16x16x32_bf16 v[90:93], v[154:157], v[186:189], v[90:93]
	v_mfma_f32_16x16x32_bf16 v[118:121], v[146:149], v[194:197], v[118:121]
	v_mfma_f32_16x16x32_bf16 v[98:101], v[154:157], v[194:197], v[98:101]
	v_mfma_f32_16x16x32_bf16 v[126:129], v[146:149], v[202:205], v[126:129]
	v_mfma_f32_16x16x32_bf16 v[110:113], v[154:157], v[202:205], v[110:113]
	v_mfma_f32_16x16x32_bf16 v[122:125], v[146:149], v[210:213], v[122:125]
	v_mfma_f32_16x16x32_bf16 v[114:117], v[154:157], v[210:213], v[114:117]
	v_mfma_f32_16x16x32_bf16 v[94:97], v[150:153], v[190:193], v[94:97]
	v_mfma_f32_16x16x32_bf16 v[90:93], v[158:161], v[190:193], v[90:93]
	v_mfma_f32_16x16x32_bf16 v[118:121], v[150:153], v[198:201], v[118:121]
	v_mfma_f32_16x16x32_bf16 v[98:101], v[158:161], v[198:201], v[98:101]
	v_mfma_f32_16x16x32_bf16 v[126:129], v[150:153], v[206:209], v[126:129]
	v_mfma_f32_16x16x32_bf16 v[110:113], v[158:161], v[206:209], v[110:113]
	v_mfma_f32_16x16x32_bf16 v[122:125], v[150:153], v[214:217], v[122:125]
	v_mfma_f32_16x16x32_bf16 v[114:117], v[158:161], v[214:217], v[114:117]
	s_setprio 0
	s_setprio 1
	v_mfma_f32_16x16x32_bf16 v[38:41], v[170:173], v[186:189], v[38:41]
	v_mfma_f32_16x16x32_bf16 v[34:37], v[178:181], v[186:189], v[34:37]
	v_mfma_f32_16x16x32_bf16 v[66:69], v[170:173], v[194:197], v[66:69]
	v_mfma_f32_16x16x32_bf16 v[46:49], v[178:181], v[194:197], v[46:49]
	v_mfma_f32_16x16x32_bf16 v[78:81], v[170:173], v[202:205], v[78:81]
	v_mfma_f32_16x16x32_bf16 v[62:65], v[178:181], v[202:205], v[62:65]
	v_mfma_f32_16x16x32_bf16 v[106:109], v[170:173], v[210:213], v[106:109]
	v_mfma_f32_16x16x32_bf16 v[102:105], v[178:181], v[210:213], v[102:105]
	v_mfma_f32_16x16x32_bf16 v[38:41], v[174:177], v[190:193], v[38:41]
	v_mfma_f32_16x16x32_bf16 v[34:37], v[182:185], v[190:193], v[34:37]
	v_mfma_f32_16x16x32_bf16 v[66:69], v[174:177], v[198:201], v[66:69]
	v_mfma_f32_16x16x32_bf16 v[46:49], v[182:185], v[198:201], v[46:49]
	v_mfma_f32_16x16x32_bf16 v[78:81], v[174:177], v[206:209], v[78:81]
	v_mfma_f32_16x16x32_bf16 v[62:65], v[182:185], v[206:209], v[62:65]
	v_mfma_f32_16x16x32_bf16 v[106:109], v[174:177], v[214:217], v[106:109]
	v_mfma_f32_16x16x32_bf16 v[102:105], v[182:185], v[214:217], v[102:105]
	s_setprio 0
	s_waitcnt vmcnt(8)
	s_barrier
; #define PG8_STAGE(bufoff, gbase, voff) do { _Pragma("unroll") for (int _i = 0; _i < 2; ++_i) \
;         __builtin_amdgcn_global_load_lds((const unsigned*)((const char*)(gbase) + (voff)[_i]), (LAS unsigned*)(lds + (bufoff) + ldsw + _i * 8192), 16, 0, 0); } while (0)
; #define PG8_LDA(dst, b, h) do { _Pragma("unroll") for (int m = 0; m < 4; ++m) _Pragma("unroll") for (int k = 0; k < 2; ++k) dst[m][k] = *(const LAS bf16x8*)(lds + PG8_SA(b, h) + aoff + m * 2048 + k * 1024); } while (0)
; #define PG8_LDB(dst, b, h) do { _Pragma("unroll") for (int n = 0; n < 2; ++n) _Pragma("unroll") for (int k = 0; k < 2; ++k) dst[n][k] = *(const LAS bf16x8*)(lds + PG8_SB(b, h) + boff + n * 2048 + k * 1024); } while (0)
; #define PG8_MMA(ai, bj, At, Bt) do { __builtin_amdgcn_s_setprio(1); _Pragma("unroll") for (int m = 0; m < 4; ++m) _Pragma("unroll") for (int n = 0; n < 2; ++n) _Pragma("unroll") for (int k = 0; k < 2; ++k) \
;         acc[ai][bj][m][n] = __builtin_amdgcn_mfma_f32_16x16x32_bf16(Bt[n][k], At[m][k], acc[ai][bj][m][n], 0, 0, 0); __builtin_amdgcn_s_setprio(0); } while (0)
; #define PG8_WAIT_V(n) asm volatile("s_waitcnt vmcnt(" #n ")" ::: "memory")
; #define PG8_WAIT_L(n) asm volatile("s_waitcnt lgkmcnt(" #n ")" ::: "memory")
; #define PG8_BAR __builtin_amdgcn_s_barrier()
; #define PG8_SCHED __builtin_amdgcn_sched_barrier(0)
; template <class Epi, class Sched, bool ALIGN_EPI, class Hook = NoHook>
; __device__ __forceinline__ void gemm_phase(LAS unsigned char* lds, const Gemm g, const Sched& S, const Epi& E, const Hook& H = Hook()) {
;     ...
;             PG8_LDB(B0, 1, 0); PG8_LDB(B1, 1, 1); PG8_SCHED; PG8_LDA(At, 1, 0); PG8_STAGE(PG8_SA(0, 1), a2 + hA, voffA);
;             PG8_WAIT_V(8); PG8_WAIT_L(0); PG8_BAR; PG8_MMA(0, 0, At, B0); PG8_MMA(0, 1, At, B1); PG8_BAR; PG8_SCHED;
;             PG8_LDA(At, 1, 1); PG8_STAGE(PG8_SB(1, 0), b3, voffB); PG8_STAGE(PG8_SB(1, 1), b3 + hB, voffB); PG8_STAGE(PG8_SA(1, 0), a3, voffA);
;             PG8_WAIT_V(8); PG8_WAIT_L(0); PG8_BAR; PG8_MMA(1, 0, At, B0); PG8_MMA(1, 1, At, B1); PG8_BAR; PG8_SCHED;
;         }
	ds_read_b128 v[146:149], v143
	ds_read_b128 v[150:153], v143 offset:1024
	s_add_u32 s16, s16, 0x2b0000
	s_addc_u32 s17, s17, 0
	s_mov_b32 m0, s29
	s_nop 0
	global_load_lds_dwordx4 v130, s[16:17]
	ds_read_b128 v[154:157], v143 offset:2048
	ds_read_b128 v[158:161], v143 offset:3072
	ds_read_b128 v[170:173], v144
	ds_read_b128 v[174:177], v144 offset:1024
	ds_read_b128 v[178:181], v144 offset:2048
	ds_read_b128 v[182:185], v144 offset:3072
	ds_read_b128 v[186:189], v142 offset:32768
	s_mov_b32 m0, s39
	s_nop 0
	global_load_lds_dwordx4 v132, s[16:17]
	ds_read_b128 v[190:193], v142 offset:33792
	ds_read_b128 v[194:197], v142 offset:34816
	ds_read_b128 v[198:201], v142 offset:35840
	ds_read_b128 v[202:205], v142 offset:36864
	ds_read_b128 v[206:209], v142 offset:37888
	ds_read_b128 v[210:213], v142 offset:38912
	ds_read_b128 v[214:217], v142 offset:39936
	s_waitcnt lgkmcnt(0)
	s_barrier
	s_setprio 1
	s_waitcnt lgkmcnt(0)
	v_mfma_f32_16x16x32_bf16 v[82:85], v[146:149], v[186:189], v[82:85]
	v_mfma_f32_16x16x32_bf16 v[54:57], v[154:157], v[186:189], v[54:57]
	v_mfma_f32_16x16x32_bf16 v[58:61], v[146:149], v[194:197], v[58:61]
	v_mfma_f32_16x16x32_bf16 v[42:45], v[154:157], v[194:197], v[42:45]
	v_mfma_f32_16x16x32_bf16 v[70:73], v[146:149], v[202:205], v[70:73]
	v_mfma_f32_16x16x32_bf16 v[50:53], v[154:157], v[202:205], v[50:53]
	v_mfma_f32_16x16x32_bf16 v[86:89], v[146:149], v[210:213], v[86:89]
	v_mfma_f32_16x16x32_bf16 v[74:77], v[154:157], v[210:213], v[74:77]
	v_mfma_f32_16x16x32_bf16 v[82:85], v[150:153], v[190:193], v[82:85]
	v_mfma_f32_16x16x32_bf16 v[54:57], v[158:161], v[190:193], v[54:57]
	v_mfma_f32_16x16x32_bf16 v[58:61], v[150:153], v[198:201], v[58:61]
	v_mfma_f32_16x16x32_bf16 v[42:45], v[158:161], v[198:201], v[42:45]
	v_mfma_f32_16x16x32_bf16 v[70:73], v[150:153], v[206:209], v[70:73]
	v_mfma_f32_16x16x32_bf16 v[50:53], v[158:161], v[206:209], v[50:53]
	v_mfma_f32_16x16x32_bf16 v[86:89], v[150:153], v[214:217], v[86:89]
	v_mfma_f32_16x16x32_bf16 v[74:77], v[158:161], v[214:217], v[74:77]
	s_setprio 0
	s_setprio 1
	v_mfma_f32_16x16x32_bf16 v[14:17], v[170:173], v[186:189], v[14:17]
	v_mfma_f32_16x16x32_bf16 v[2:5], v[178:181], v[186:189], v[2:5]
	v_mfma_f32_16x16x32_bf16 v[18:21], v[170:173], v[194:197], v[18:21]
	v_mfma_f32_16x16x32_bf16 v[6:9], v[178:181], v[194:197], v[6:9]
	v_mfma_f32_16x16x32_bf16 v[22:25], v[170:173], v[202:205], v[22:25]
	v_mfma_f32_16x16x32_bf16 v[10:13], v[178:181], v[202:205], v[10:13]
	v_mfma_f32_16x16x32_bf16 v[30:33], v[170:173], v[210:213], v[30:33]
	v_mfma_f32_16x16x32_bf16 v[26:29], v[178:181], v[210:213], v[26:29]
	v_mfma_f32_16x16x32_bf16 v[14:17], v[174:177], v[190:193], v[14:17]
	v_mfma_f32_16x16x32_bf16 v[2:5], v[182:185], v[190:193], v[2:5]
	v_mfma_f32_16x16x32_bf16 v[18:21], v[174:177], v[198:201], v[18:21]
	v_mfma_f32_16x16x32_bf16 v[6:9], v[182:185], v[198:201], v[6:9]
	v_mfma_f32_16x16x32_bf16 v[22:25], v[174:177], v[206:209], v[22:25]
	v_mfma_f32_16x16x32_bf16 v[10:13], v[182:185], v[206:209], v[10:13]
	v_mfma_f32_16x16x32_bf16 v[30:33], v[174:177], v[214:217], v[30:33]
	v_mfma_f32_16x16x32_bf16 v[26:29], v[182:185], v[214:217], v[26:29]
	s_setprio 0
	s_waitcnt vmcnt(8)
	s_barrier
	s_mov_b32 m0, s36
	s_add_u32 s52, s10, s2
	s_addc_u32 s53, s11, s3
	s_add_u32 s10, s10, 0x2b0080
	ds_read_b128 v[186:189], v142 offset:49152
	ds_read_b128 v[190:193], v142 offset:50176
	global_load_lds_dwordx4 v162, s[52:53]
	ds_read_b128 v[194:197], v142 offset:51200
	s_mov_b32 m0, s44
	s_addc_u32 s11, s11, 0
	global_load_lds_dwordx4 v134, s[52:53]
	ds_read_b128 v[198:201], v142 offset:52224
	s_mov_b32 m0, s37
	s_nop 0
	global_load_lds_dwordx4 v162, s[10:11]
	ds_read_b128 v[202:205], v142 offset:53248
	s_mov_b32 m0, s45
	s_nop 0
	global_load_lds_dwordx4 v134, s[10:11]
	ds_read_b128 v[206:209], v142 offset:54272
	s_mov_b32 m0, s41
	s_nop 0
	global_load_lds_dwordx4 v130, s[54:55]
	ds_read_b128 v[210:213], v142 offset:55296
	s_mov_b32 m0, s42
	s_nop 0
	global_load_lds_dwordx4 v132, s[54:55]
	ds_read_b128 v[214:217], v142 offset:56320
	s_waitcnt lgkmcnt(0)
	s_barrier
	s_setprio 1
	s_waitcnt lgkmcnt(0)
	v_mfma_f32_16x16x32_bf16 v[94:97], v[146:149], v[186:189], v[94:97]
	v_mfma_f32_16x16x32_bf16 v[90:93], v[154:157], v[186:189], v[90:93]
	v_mfma_f32_16x16x32_bf16 v[118:121], v[146:149], v[194:197], v[118:121]
	v_mfma_f32_16x16x32_bf16 v[98:101], v[154:157], v[194:197], v[98:101]
	v_mfma_f32_16x16x32_bf16 v[126:129], v[146:149], v[202:205], v[126:129]
	v_mfma_f32_16x16x32_bf16 v[110:113], v[154:157], v[202:205], v[110:113]
	v_mfma_f32_16x16x32_bf16 v[122:125], v[146:149], v[210:213], v[122:125]
	v_mfma_f32_16x16x32_bf16 v[114:117], v[154:157], v[210:213], v[114:117]
	v_mfma_f32_16x16x32_bf16 v[94:97], v[150:153], v[190:193], v[94:97]
	v_mfma_f32_16x16x32_bf16 v[90:93], v[158:161], v[190:193], v[90:93]
	v_mfma_f32_16x16x32_bf16 v[118:121], v[150:153], v[198:201], v[118:121]
	v_mfma_f32_16x16x32_bf16 v[98:101], v[158:161], v[198:201], v[98:101]
	v_mfma_f32_16x16x32_bf16 v[126:129], v[150:153], v[206:209], v[126:129]
	v_mfma_f32_16x16x32_bf16 v[110:113], v[158:161], v[206:209], v[110:113]
	v_mfma_f32_16x16x32_bf16 v[122:125], v[150:153], v[214:217], v[122:125]
	v_mfma_f32_16x16x32_bf16 v[114:117], v[158:161], v[214:217], v[114:117]
	s_setprio 0
	s_setprio 1
	v_mfma_f32_16x16x32_bf16 v[38:41], v[170:173], v[186:189], v[38:41]
	v_mfma_f32_16x16x32_bf16 v[34:37], v[178:181], v[186:189], v[34:37]
	v_mfma_f32_16x16x32_bf16 v[66:69], v[170:173], v[194:197], v[66:69]
	v_mfma_f32_16x16x32_bf16 v[46:49], v[178:181], v[194:197], v[46:49]
	v_mfma_f32_16x16x32_bf16 v[78:81], v[170:173], v[202:205], v[78:81]
	v_mfma_f32_16x16x32_bf16 v[62:65], v[178:181], v[202:205], v[62:65]
	v_mfma_f32_16x16x32_bf16 v[106:109], v[170:173], v[210:213], v[106:109]
	v_mfma_f32_16x16x32_bf16 v[102:105], v[178:181], v[210:213], v[102:105]
	v_mfma_f32_16x16x32_bf16 v[38:41], v[174:177], v[190:193], v[38:41]
	v_mfma_f32_16x16x32_bf16 v[34:37], v[182:185], v[190:193], v[34:37]
	v_mfma_f32_16x16x32_bf16 v[66:69], v[174:177], v[198:201], v[66:69]
	v_mfma_f32_16x16x32_bf16 v[46:49], v[182:185], v[198:201], v[46:49]
	v_mfma_f32_16x16x32_bf16 v[78:81], v[174:177], v[206:209], v[78:81]
	v_mfma_f32_16x16x32_bf16 v[62:65], v[182:185], v[206:209], v[62:65]
	v_mfma_f32_16x16x32_bf16 v[106:109], v[174:177], v[214:217], v[106:109]
	v_mfma_f32_16x16x32_bf16 v[102:105], v[182:185], v[214:217], v[102:105]
	s_setprio 0
	s_waitcnt vmcnt(8)
	s_barrier
	s_add_i32 s18, s18, 2
	s_add_u32 s4, s4, 0x100
	s_addc_u32 s5, s5, 0
	s_cmpk_gt_u32 s18, 0xa9
	s_cbranch_scc0 .LBB0_1406
	s_branch .Lmy_d1406X
